# wc_b workspace stored fragment-major (MFMA lane order) in P0 so the C item's 20 mixing-matrix fragment loads are 1 KB contiguous each instead of 64 row-strided 16-byte pieces
# speedup vs baseline: 1.0240x; 1.0069x over previous
.LBB0_15:
	s_or_b64 exec, exec, s[2:3]
	s_mov_b32 s0, 0x20000
	v_cmp_gt_i32_e32 vcc, s0, v2
	s_and_saveexec_b64 s[0:1], vcc
	s_cbranch_execz .LBB0_20
	s_waitcnt lgkmcnt(0)
	s_lshl_b32 s2, s46, 9
	v_ashrrev_i32_e32 v3, 31, v2
	s_ashr_i32 s3, s2, 31
	v_and_b32_e32 v8, 0x7f, v1
	v_lshl_add_u64 v[4:5], v[2:3], 2, s[90:91]
	s_lshl_b64 s[8:9], s[2:3], 2
	v_and_b32_e32 v6, 0xfffff007, v2
	v_bfe_u32 v9, v2, 4, 3
	v_lshl_or_b32 v6, v9, 9, v6
	v_bfe_u32 v9, v2, 3, 1
	v_lshl_or_b32 v6, v9, 8, v6
	v_bfe_u32 v9, v2, 7, 5
	v_lshl_or_b32 v6, v9, 3, v6
	v_mov_b32_e32 v7, 0
	v_lshl_add_u64 v[6:7], v[6:7], 1, s[56:57]
	s_lshl_b64 s[10:11], s[2:3], 1
	s_mov_b64 s[12:13], 0
	s_movk_i32 s3, 0x7fff
	s_mov_b32 s5, 0x1ffff
	s_branch .LBB0_18

.LBB0_779:
	v_mov_b32_e32 v43, v0
	s_ashr_i32 s5, s3, 31
	v_ashrrev_i32_e32 v44, 7, v43
	s_waitcnt vmcnt(2)
	v_add_u32_e32 v164, s2, v44
	v_ashrrev_i32_e32 v165, 31, v164
	v_and_b32_e32 v168, 31, v43
	s_waitcnt vmcnt(0)
	v_lshlrev_b64 v[2:3], 15, v[164:165]
	v_bfe_u32 v169, v43, 5, 1
	v_lshl_add_u64 v[2:3], s[56:57], 0, v[2:3]
	v_and_b32_e32 v18, 63, v43
	v_lshlrev_b32_e32 v18, 4, v18
	v_lshlrev_b32_e32 v154, 4, v169
	v_add_u32_e32 v18, 0x1000, v18
	v_add_co_u32_e32 v18, vcc, v2, v18
	s_nop 1
	v_addc_co_u32_e32 v19, vcc, 0, v3, vcc
	v_add_co_u32_e32 v20, vcc, s14, v18
	v_ashrrev_i32_e32 v45, 2, v43
	s_nop 0
	v_addc_co_u32_e32 v21, vcc, 0, v19, vcc
	v_add_co_u32_e32 v22, vcc, s17, v18
	global_load_dwordx4 v[2:5], v[18:19], off offset:-4096
	global_load_dwordx4 v[6:9], v[20:21], off offset:-4096
	v_addc_co_u32_e32 v23, vcc, 0, v19, vcc
	v_add_co_u32_e32 v24, vcc, s30, v18
	global_load_dwordx4 v[10:13], v[22:23], off offset:-4096
	s_nop 0
	v_addc_co_u32_e32 v25, vcc, 0, v19, vcc
	global_load_dwordx4 v[14:17], v[24:25], off offset:-4096
	global_load_dwordx4 v[138:141], v[18:19], off offset:-3072
	global_load_dwordx4 v[142:145], v[20:21], off offset:-3072
	global_load_dwordx4 v[146:149], v[22:23], off offset:-3072
	global_load_dwordx4 v[150:153], v[24:25], off offset:-3072
	global_load_dwordx4 v[126:129], v[20:21], off offset:-2048
	global_load_dwordx4 v[130:133], v[22:23], off offset:-2048
	global_load_dwordx4 v[134:137], v[24:25], off offset:-2048
	global_load_dwordx4 v[114:117], v[20:21], off offset:-1024
	global_load_dwordx4 v[118:121], v[22:23], off offset:-1024
	global_load_dwordx4 v[122:125], v[24:25], off offset:-1024
	global_load_dwordx4 v[106:109], v[22:23], off
	global_load_dwordx4 v[110:113], v[24:25], off
	global_load_dwordx4 v[98:101], v[22:23], off offset:1024
	global_load_dwordx4 v[102:105], v[24:25], off offset:1024
	global_load_dwordx4 v[94:97], v[24:25], off offset:2048
	global_load_dwordx4 v[90:93], v[24:25], off offset:3072
	v_add_u32_e32 v18, s3, v45
	v_ashrrev_i32_e32 v19, 31, v18
	v_lshlrev_b32_e32 v20, 6, v43
	v_lshlrev_b64 v[18:19], 12, v[18:19]
	v_and_b32_e32 v46, 0xc0, v20
	v_lshl_add_u64 v[18:19], s[60:61], 0, v[18:19]
	v_lshlrev_b32_e32 v20, 1, v46
	v_mov_b32_e32 v21, v155
	v_lshl_add_u64 v[34:35], v[18:19], 0, v[20:21]
	global_load_dwordx4 v[18:21], v[34:35], off offset:3632
	global_load_dwordx4 v[22:25], v[34:35], off offset:3616
	global_load_dwordx4 v[26:29], v[34:35], off offset:3600
	global_load_dwordx4 v[30:33], v[34:35], off offset:3584
	global_load_dwordx4 v[36:39], v[34:35], off offset:3680
	global_load_dwordx4 v[202:205], v[34:35], off offset:3664
	global_load_dwordx4 v[48:51], v[34:35], off offset:3648
	global_load_dwordx4 v[206:209], v[34:35], off offset:3696
	v_and_b32_e32 v215, 31, v0
	v_add_u32_e32 v215, s3, v215
	v_lshlrev_b32_e32 v215, 12, v215
	v_and_b32_e32 v245, 0x1c0, v0
	v_add_u32_e32 v215, v215, v245
	v_bfe_u32 v245, v0, 5, 1
	v_lshl_add_u32 v245, v245, 3, v215
	v_bfe_u32 v215, v0, 5, 1
	v_lshl_add_u32 v215, v215, 3, v245
	global_load_dwordx4 v[216:219], v215, s[60:61] offset:3072
	global_load_dwordx4 v[220:223], v215, s[60:61] offset:3104
	s_add_u32 s98, s60, 0x20000
	s_addc_u32 s99, s61, 0
	global_load_dwordx4 v[224:227], v215, s[98:99] offset:3072
	global_load_dwordx4 v[228:231], v215, s[98:99] offset:3104
	s_add_u32 s100, s60, 0x40000
	s_addc_u32 s101, s61, 0
	global_load_dwordx4 v[232:235], v215, s[100:101] offset:3072
	global_load_dwordx4 v[236:239], v215, s[100:101] offset:3104
	s_add_u32 s98, s60, 0x60000
	s_addc_u32 s99, s61, 0
	global_load_dwordx4 v[252:255], v215, s[98:99] offset:3072
	global_load_dwordx2 v[240:241], v245, s[98:99] offset:3104
	global_load_dwordx2 v[246:247], v245, s[98:99] offset:3120
	v_lshrrev_b32_e32 v42, 5, v43
	s_add_i32 s4, s4, s46
	s_waitcnt vmcnt(16)
	v_lshlrev_b32_e32 v178, 16, v18
	s_waitcnt vmcnt(15)
	v_lshlrev_b32_e32 v186, 16, v22
	s_waitcnt vmcnt(14)
	v_lshlrev_b32_e32 v194, 16, v26
	s_waitcnt vmcnt(13)
	v_lshlrev_b32_e32 v200, 16, v30
	v_and_b32_e32 v199, 0xffff0000, v30
	v_add_f32_e32 v30, 0, v200
	v_lshlrev_b32_e32 v198, 16, v31
	v_add_f32_e32 v30, v30, v199
	v_and_b32_e32 v197, 0xffff0000, v31
	v_mul_f32_e32 v31, v199, v199
	v_add_f32_e32 v30, v30, v198
	v_lshlrev_b32_e32 v196, 16, v32
	v_fmac_f32_e32 v31, v200, v200
	v_add_f32_e32 v30, v30, v197
	v_and_b32_e32 v195, 0xffff0000, v32
	v_fmac_f32_e32 v31, v198, v198
	v_add_f32_e32 v30, v30, v196
	v_lshlrev_b32_e32 v193, 16, v33
	v_fmac_f32_e32 v31, v197, v197
	v_add_f32_e32 v30, v30, v195
	v_and_b32_e32 v191, 0xffff0000, v33
	v_fmac_f32_e32 v31, v196, v196
	v_add_f32_e32 v30, v30, v193
	v_fmac_f32_e32 v31, v195, v195
	v_add_f32_e32 v30, v30, v191
	v_fmac_f32_e32 v31, v193, v193
	v_and_b32_e32 v192, 0xffff0000, v26
	v_add_f32_e32 v26, v30, v194
	v_fmac_f32_e32 v31, v191, v191
	v_lshlrev_b32_e32 v190, 16, v27
	v_add_f32_e32 v26, v26, v192
	v_and_b32_e32 v189, 0xffff0000, v27
	v_fmac_f32_e32 v31, v194, v194
	v_add_f32_e32 v26, v26, v190
	v_lshlrev_b32_e32 v188, 16, v28
	v_fmac_f32_e32 v31, v192, v192
	v_add_f32_e32 v26, v26, v189
	v_and_b32_e32 v187, 0xffff0000, v28
	v_fmac_f32_e32 v31, v190, v190
	v_add_f32_e32 v26, v26, v188
	v_lshlrev_b32_e32 v184, 16, v29
	v_fmac_f32_e32 v31, v189, v189
	v_add_f32_e32 v26, v26, v187
	v_and_b32_e32 v182, 0xffff0000, v29
	v_fmac_f32_e32 v31, v188, v188
	v_add_f32_e32 v26, v26, v184
	v_fmac_f32_e32 v31, v187, v187
	v_add_f32_e32 v26, v26, v182
	v_fmac_f32_e32 v31, v184, v184
	v_and_b32_e32 v185, 0xffff0000, v22
	v_add_f32_e32 v22, v26, v186
	v_fmac_f32_e32 v31, v182, v182
	v_lshlrev_b32_e32 v183, 16, v23
	v_add_f32_e32 v22, v22, v185
	v_and_b32_e32 v179, 0xffff0000, v23
	v_fmac_f32_e32 v31, v186, v186
	v_add_f32_e32 v22, v22, v183
	v_lshlrev_b32_e32 v177, 16, v24
	v_fmac_f32_e32 v31, v185, v185
	v_add_f32_e32 v22, v22, v179
	v_and_b32_e32 v175, 0xffff0000, v24
	v_fmac_f32_e32 v31, v183, v183
	v_add_f32_e32 v22, v22, v177
	v_lshlrev_b32_e32 v173, 16, v25
	v_fmac_f32_e32 v31, v179, v179
	v_add_f32_e32 v22, v22, v175
	v_and_b32_e32 v171, 0xffff0000, v25
	v_fmac_f32_e32 v31, v177, v177
	v_add_f32_e32 v22, v22, v173
	v_fmac_f32_e32 v31, v175, v175
	v_add_f32_e32 v22, v22, v171
	v_fmac_f32_e32 v31, v173, v173
	v_and_b32_e32 v176, 0xffff0000, v18
	v_add_f32_e32 v18, v22, v178
	v_fmac_f32_e32 v31, v171, v171
	v_lshlrev_b32_e32 v174, 16, v19
	v_add_f32_e32 v18, v18, v176
	v_and_b32_e32 v172, 0xffff0000, v19
	v_fmac_f32_e32 v31, v178, v178
	v_add_f32_e32 v18, v18, v174
	v_lshlrev_b32_e32 v167, 16, v20
	v_fmac_f32_e32 v31, v176, v176
	v_add_f32_e32 v18, v18, v172
	v_and_b32_e32 v165, 0xffff0000, v20
	v_fmac_f32_e32 v31, v174, v174
	v_add_f32_e32 v18, v18, v167
	v_lshlrev_b32_e32 v64, 16, v21
	v_fmac_f32_e32 v31, v172, v172
	v_add_f32_e32 v18, v18, v165
	v_and_b32_e32 v62, 0xffff0000, v21
	v_fmac_f32_e32 v31, v167, v167
	v_add_f32_e32 v18, v18, v64
	v_fmac_f32_e32 v31, v165, v165
	v_add_f32_e32 v18, v18, v62
	s_waitcnt vmcnt(10)
	v_lshlrev_b32_e32 v170, 16, v48
	v_fmac_f32_e32 v31, v64, v64
	v_and_b32_e32 v166, 0xffff0000, v48
	v_add_f32_e32 v18, v18, v170
	v_fmac_f32_e32 v31, v62, v62
	v_lshlrev_b32_e32 v65, 16, v49
	v_add_f32_e32 v18, v18, v166
	v_and_b32_e32 v63, 0xffff0000, v49
	v_fmac_f32_e32 v31, v170, v170
	v_add_f32_e32 v18, v18, v65
	v_lshlrev_b32_e32 v60, 16, v50
	v_fmac_f32_e32 v31, v166, v166
	v_add_f32_e32 v18, v18, v63
	v_and_b32_e32 v59, 0xffff0000, v50
	v_fmac_f32_e32 v31, v65, v65
	v_add_f32_e32 v18, v18, v60
	v_lshlrev_b32_e32 v57, 16, v51
	v_fmac_f32_e32 v31, v63, v63
	v_add_f32_e32 v18, v18, v59
	v_and_b32_e32 v55, 0xffff0000, v51
	v_fmac_f32_e32 v31, v60, v60
	v_add_f32_e32 v18, v18, v57
	v_fmac_f32_e32 v31, v59, v59
	v_add_f32_e32 v18, v18, v55
	v_lshlrev_b32_e32 v61, 16, v202
	v_fmac_f32_e32 v31, v57, v57
	v_and_b32_e32 v58, 0xffff0000, v202
	v_add_f32_e32 v18, v18, v61
	v_fmac_f32_e32 v31, v55, v55
	v_lshlrev_b32_e32 v56, 16, v203
	v_add_f32_e32 v18, v18, v58
	v_and_b32_e32 v54, 0xffff0000, v203
	v_fmac_f32_e32 v31, v61, v61
	v_add_f32_e32 v18, v18, v56
	v_lshlrev_b32_e32 v53, 16, v204
	v_fmac_f32_e32 v31, v58, v58
	v_add_f32_e32 v18, v18, v54
	v_and_b32_e32 v51, 0xffff0000, v204
	v_fmac_f32_e32 v31, v56, v56
	v_add_f32_e32 v18, v18, v53
	v_lshlrev_b32_e32 v49, 16, v205
	v_fmac_f32_e32 v31, v54, v54
	v_add_f32_e32 v18, v18, v51
	v_and_b32_e32 v47, 0xffff0000, v205
	v_fmac_f32_e32 v31, v53, v53
	v_add_f32_e32 v18, v18, v49
	v_fmac_f32_e32 v31, v51, v51
	v_add_f32_e32 v18, v18, v47
	v_lshlrev_b32_e32 v52, 16, v36
	v_fmac_f32_e32 v31, v49, v49
	v_and_b32_e32 v50, 0xffff0000, v36
	v_add_f32_e32 v18, v18, v52
	v_fmac_f32_e32 v31, v47, v47
	v_lshlrev_b32_e32 v48, 16, v37
	v_add_f32_e32 v18, v18, v50
	v_fmac_f32_e32 v31, v52, v52
	v_add_f32_e32 v18, v18, v48
	v_and_b32_e32 v37, 0xffff0000, v37
	v_fmac_f32_e32 v31, v50, v50
	v_lshlrev_b32_e32 v34, 16, v38
	v_mov_b32_e32 v35, v37
	v_add_f32_e32 v20, v18, v37
	v_fmac_f32_e32 v31, v48, v48
	v_and_b32_e32 v24, 0xffff0000, v38
	v_pk_mul_f32 v[18:19], v[34:35], v[34:35]
	v_add_f32_e32 v20, v20, v34
	v_lshlrev_b32_e32 v25, 16, v39
	v_add_f32_e32 v19, v19, v31
	v_add_f32_e32 v20, v20, v24
	v_add_f32_e32 v21, v18, v19
	v_pk_mul_f32 v[18:19], v[24:25], v[24:25]
	v_add_f32_e32 v20, v20, v25
	v_and_b32_e32 v33, 0xffff0000, v39
	v_add_f32_e32 v18, v18, v21
	s_waitcnt vmcnt(9)
	v_lshlrev_b32_e32 v28, 16, v206
	v_mov_b32_e32 v29, v33
	v_add_f32_e32 v20, v20, v33
	v_add_f32_e32 v21, v19, v18
	v_and_b32_e32 v22, 0xffff0000, v206
	v_pk_mul_f32 v[18:19], v[28:29], v[28:29]
	v_add_f32_e32 v20, v20, v28
	v_lshlrev_b32_e32 v23, 16, v207
	v_add_f32_e32 v19, v19, v21
	v_add_f32_e32 v20, v20, v22
	v_add_f32_e32 v21, v18, v19
	v_pk_mul_f32 v[18:19], v[22:23], v[22:23]
	v_add_f32_e32 v29, v20, v23
	v_and_b32_e32 v31, 0xffff0000, v207
	v_add_f32_e32 v18, v18, v21
	v_lshlrev_b32_e32 v26, 16, v208
	v_mov_b32_e32 v27, v31
	v_add_f32_e32 v29, v29, v31
	v_and_b32_e32 v36, s0, v38
	v_add_f32_e32 v18, v19, v18
	v_and_b32_e32 v20, 0xffff0000, v208
	v_pk_mul_f32 v[38:39], v[26:27], v[26:27]
	v_add_f32_e32 v27, v29, v26
	v_lshlrev_b32_e32 v21, 16, v209
	v_add_f32_e32 v18, v39, v18
	v_add_f32_e32 v27, v27, v20
	v_and_b32_e32 v29, 64, v181
	v_add_f32_e32 v18, v38, v18
	v_pk_mul_f32 v[40:41], v[20:21], v[20:21]
	v_add_f32_e32 v39, v27, v21
	v_xor_b32_e32 v27, 1, v181
	v_add_u32_e32 v29, 64, v29
	v_and_b32_e32 v19, 0xffff0000, v209
	v_add_f32_e32 v18, v40, v18
	v_cmp_lt_i32_e32 vcc, v27, v29
	v_add_f32_e32 v18, v41, v18
	v_mul_f32_e32 v38, v19, v19
	v_cndmask_b32_e32 v27, v181, v27, vcc
	v_lshlrev_b32_e32 v27, 2, v27
	v_pk_add_f32 v[38:39], v[38:39], v[18:19]
	ds_bpermute_b32 v41, v27, v39
	ds_bpermute_b32 v40, v27, v38
	v_xor_b32_e32 v35, 2, v181
	v_cmp_lt_i32_e32 vcc, v35, v29
	v_and_b32_e32 v30, s0, v206
	v_mov_b32_e32 v32, v36
	v_cndmask_b32_e32 v29, v181, v35, vcc
	v_lshlrev_b32_e32 v29, 2, v29
	s_waitcnt lgkmcnt(0)
	v_pk_add_f32 v[38:39], v[38:39], v[40:41]
	ds_bpermute_b32 v41, v29, v39
	ds_bpermute_b32 v40, v29, v38
	s_waitcnt lgkmcnt(0)
	v_pk_add_f32 v[40:41], v[38:39], v[40:41]
	s_nop 0
	v_pk_mul_f32 v[38:39], v[40:41], s[22:23] op_sel_hi:[1,0]
	v_pk_fma_f32 v[36:37], v[40:41], s[22:23], v[36:37] op_sel_hi:[1,0,1] neg_lo:[1,0,0] neg_hi:[1,0,0]
	v_fma_f32 v18, -v39, v39, v38
	v_max_f32_e32 v18, 0, v18
	v_add_f32_e32 v18, 0x358637bd, v18
	v_cmp_gt_f32_e32 vcc, s33, v18
	v_mul_f32_e32 v27, 0x4b800000, v18
	v_sub_f32_e32 v29, v200, v39
	v_cndmask_b32_e32 v18, v18, v27, vcc
	v_rsq_f32_e32 v18, v18
	v_sub_f32_e32 v19, v19, v39
	v_mul_f32_e32 v27, 0x45800000, v18
	v_cndmask_b32_e32 v18, v18, v27, vcc
	v_mul_f32_e32 v29, v29, v18
	v_lshlrev_b32_e32 v27, 1, v45
	v_bfe_u32 v35, v29, 16, 1
	v_ashrrev_i32_e32 v45, 1, v43
	v_and_b32_e32 v27, 14, v27
	v_add3_u32 v29, v29, v35, s15
	v_lshl_add_u32 v35, v46, 8, 32
	v_and_b32_e32 v46, -16, v45
	v_add3_u32 v200, v35, v46, v27
	ds_write_b16_d16_hi v200, v29 offset:55296
	v_mul_f32_e64 v215, -v39, v18
	v_fma_f32 v29, v199, v18, v215
	v_cvt_pk_bf16_f32 v29, v29, v29
	v_bitop3_b32 v199, v45, 16, -16 bitop3:0x6c
	v_add3_u32 v201, v35, v199, v27
	ds_write_b16 v201, v29 offset:55552
	v_fma_f32 v29, v198, v18, v215
	v_cvt_pk_bf16_f32 v29, v29, v29
	v_bitop3_b32 v198, v45, 32, -16 bitop3:0x6c
	v_add3_u32 v202, v35, v198, v27
	ds_write_b16 v202, v29 offset:55808
	v_fma_f32 v29, v197, v18, v215
	v_cvt_pk_bf16_f32 v29, v29, v29
	v_bitop3_b32 v197, v45, 48, -16 bitop3:0x6c
	v_add3_u32 v203, v35, v197, v27
	ds_write_b16 v203, v29 offset:56064
	v_fma_f32 v29, v196, v18, v215
	v_cvt_pk_bf16_f32 v29, v29, v29
	v_bitop3_b32 v196, v45, 64, -16 bitop3:0x6c
	v_add3_u32 v204, v35, v196, v27
	ds_write_b16 v204, v29 offset:56320
	v_fma_f32 v29, v195, v18, v215
	v_cvt_pk_bf16_f32 v29, v29, v29
	v_bitop3_b32 v195, v45, s34, -16 bitop3:0x6c
	v_add3_u32 v205, v35, v195, v27
	ds_write_b16 v205, v29 offset:56576
	v_fma_f32 v29, v193, v18, v215
	v_cvt_pk_bf16_f32 v29, v29, v29
	v_bitop3_b32 v193, v45, s31, -16 bitop3:0x6c
	v_add3_u32 v206, v35, v193, v27
	ds_write_b16 v206, v29 offset:56832
	v_fma_f32 v29, v191, v18, v215
	v_cvt_pk_bf16_f32 v29, v29, v29
	v_bitop3_b32 v191, v45, s13, -16 bitop3:0x6c
	v_add3_u32 v207, v35, v191, v27
	ds_write_b16 v207, v29 offset:57088
	v_fma_f32 v29, v194, v18, v215
	v_cvt_pk_bf16_f32 v29, v29, v29
	v_bitop3_b32 v194, v45, s12, -16 bitop3:0x6c
	v_add3_u32 v208, v35, v194, v27
	ds_write_b16 v208, v29 offset:57344
	v_fma_f32 v29, v192, v18, v215
	v_cvt_pk_bf16_f32 v29, v29, v29
	v_bitop3_b32 v192, v45, s35, -16 bitop3:0x6c
	v_add3_u32 v209, v35, v192, v27
	ds_write_b16 v209, v29 offset:57600
	v_fma_f32 v29, v190, v18, v215
	v_cvt_pk_bf16_f32 v29, v29, v29
	v_bitop3_b32 v190, v45, s36, -16 bitop3:0x6c
	v_add3_u32 v210, v35, v190, v27
	ds_write_b16 v210, v29 offset:57856
	v_fma_f32 v29, v189, v18, v215
	v_cvt_pk_bf16_f32 v29, v29, v29
	v_bitop3_b32 v189, v45, s37, -16 bitop3:0x6c
	v_add3_u32 v211, v35, v189, v27
	ds_write_b16 v211, v29 offset:58112
	v_fma_f32 v29, v188, v18, v215
	v_cvt_pk_bf16_f32 v29, v29, v29
	v_bitop3_b32 v188, v45, s16, -16 bitop3:0x6c
	v_add3_u32 v212, v35, v188, v27
	ds_write_b16 v212, v29 offset:58368
	v_fma_f32 v29, v187, v18, v215
	v_cvt_pk_bf16_f32 v29, v29, v29
	v_bitop3_b32 v187, v45, s42, -16 bitop3:0x6c
	v_add3_u32 v213, v35, v187, v27
	ds_write_b16 v213, v29 offset:58624
	v_fma_f32 v29, v184, v18, v215
	v_cvt_pk_bf16_f32 v29, v29, v29
	v_bitop3_b32 v184, v45, s43, -16 bitop3:0x6c
	v_add3_u32 v214, v35, v184, v27
	ds_write_b16 v214, v29 offset:58880
	v_sub_f32_e32 v29, v182, v39
	v_mul_f32_e32 v29, v29, v18
	v_bfe_u32 v182, v29, 16, 1
	v_bitop3_b32 v45, v45, s94, -16 bitop3:0x6c
	v_add_u32_e32 v38, 0xd800, v35
	v_add3_u32 v29, v29, v182, s15
	v_add3_u32 v35, v35, v45, v27
	ds_write_b16_d16_hi v35, v29 offset:59136
	v_fma_f32 v29, v186, v18, v215
	v_cvt_pk_bf16_f32 v29, v29, v29
	ds_write_b16 v200, v29 offset:59392
	v_fma_f32 v29, v185, v18, v215
	v_cvt_pk_bf16_f32 v29, v29, v29
	ds_write_b16 v201, v29 offset:59648
	v_fma_f32 v29, v183, v18, v215
	v_cvt_pk_bf16_f32 v29, v29, v29
	ds_write_b16 v202, v29 offset:59904
	v_fma_f32 v29, v179, v18, v215
	v_cvt_pk_bf16_f32 v29, v29, v29
	ds_write_b16 v203, v29 offset:60160
	v_fma_f32 v29, v177, v18, v215
	v_cvt_pk_bf16_f32 v29, v29, v29
	ds_write_b16 v204, v29 offset:60416
	v_fma_f32 v29, v175, v18, v215
	v_cvt_pk_bf16_f32 v29, v29, v29
	ds_write_b16 v205, v29 offset:60672
	v_fma_f32 v29, v173, v18, v215
	v_cvt_pk_bf16_f32 v29, v29, v29
	ds_write_b16 v206, v29 offset:60928
	v_fma_f32 v29, v171, v18, v215
	v_cvt_pk_bf16_f32 v29, v29, v29
	ds_write_b16 v207, v29 offset:61184
	v_fma_f32 v29, v178, v18, v215
	v_cvt_pk_bf16_f32 v29, v29, v29
	ds_write_b16 v208, v29 offset:61440
	v_fma_f32 v29, v176, v18, v215
	v_cvt_pk_bf16_f32 v29, v29, v29
	ds_write_b16 v209, v29 offset:61696
	v_fma_f32 v29, v174, v18, v215
	v_cvt_pk_bf16_f32 v29, v29, v29
	ds_write_b16 v210, v29 offset:61952
	v_fma_f32 v29, v172, v18, v215
	v_cvt_pk_bf16_f32 v29, v29, v29
	ds_write_b16 v211, v29 offset:62208
	v_fma_f32 v29, v167, v18, v215
	v_cvt_pk_bf16_f32 v29, v29, v29
	ds_write_b16 v212, v29 offset:62464
	v_fma_f32 v29, v165, v18, v215
	v_cvt_pk_bf16_f32 v29, v29, v29
	ds_write_b16 v213, v29 offset:62720
	v_fma_f32 v29, v64, v18, v215
	v_cvt_pk_bf16_f32 v29, v29, v29
	ds_write_b16 v214, v29 offset:62976
	v_fma_f32 v29, v62, v18, v215
	v_cvt_pk_bf16_f32 v29, v29, v29
	ds_write_b16 v35, v29 offset:63232
	v_fma_f32 v29, v170, v18, v215
	v_cvt_pk_bf16_f32 v29, v29, v29
	ds_write_b16 v200, v29 offset:63488
	v_fma_f32 v29, v166, v18, v215
	v_cvt_pk_bf16_f32 v29, v29, v29
	ds_write_b16 v201, v29 offset:63744
	v_fma_f32 v29, v65, v18, v215
	v_cvt_pk_bf16_f32 v29, v29, v29
	ds_write_b16 v202, v29 offset:64000
	v_fma_f32 v29, v63, v18, v215
	v_cvt_pk_bf16_f32 v29, v29, v29
	ds_write_b16 v203, v29 offset:64256
	v_fma_f32 v29, v60, v18, v215
	v_cvt_pk_bf16_f32 v29, v29, v29
	ds_write_b16 v204, v29 offset:64512
	v_fma_f32 v29, v59, v18, v215
	v_cvt_pk_bf16_f32 v29, v29, v29
	ds_write_b16 v205, v29 offset:64768
	v_fma_f32 v29, v57, v18, v215
	v_cvt_pk_bf16_f32 v29, v29, v29
	ds_write_b16 v206, v29 offset:65024
	v_fma_f32 v29, v55, v18, v215
	v_cvt_pk_bf16_f32 v29, v29, v29
	ds_write_b16 v207, v29 offset:65280
	v_fma_f32 v29, v61, v18, v215
	v_cvt_pk_bf16_f32 v29, v29, v29
	v_add3_u32 v35, v38, v194, v27
	ds_write_b16 v35, v29 offset:10240
	v_fma_f32 v29, v58, v18, v215
	v_cvt_pk_bf16_f32 v29, v29, v29
	v_add3_u32 v55, v38, v192, v27
	ds_write_b16 v55, v29 offset:10496
	v_fma_f32 v29, v56, v18, v215
	v_cvt_pk_bf16_f32 v29, v29, v29
	v_add3_u32 v56, v38, v190, v27
	ds_write_b16 v56, v29 offset:10752
	v_fma_f32 v29, v54, v18, v215
	v_cvt_pk_bf16_f32 v29, v29, v29
	v_add3_u32 v54, v38, v189, v27
	ds_write_b16 v54, v29 offset:11008
	v_fma_f32 v29, v53, v18, v215
	v_cvt_pk_bf16_f32 v29, v29, v29
	v_add3_u32 v53, v38, v188, v27
	ds_write_b16 v53, v29 offset:11264
	v_fma_f32 v29, v51, v18, v215
	v_cvt_pk_bf16_f32 v29, v29, v29
	v_add3_u32 v51, v38, v187, v27
	ds_write_b16 v51, v29 offset:11520
	v_fma_f32 v29, v49, v18, v215
	v_cvt_pk_bf16_f32 v29, v29, v29
	v_add3_u32 v49, v38, v184, v27
	ds_write_b16 v49, v29 offset:11776
	v_fma_f32 v29, v47, v18, v215
	v_cvt_pk_bf16_f32 v29, v29, v29
	v_add3_u32 v45, v38, v45, v27
	ds_write_b16 v45, v29 offset:12032
	v_fma_f32 v29, v52, v18, v215
	v_cvt_pk_bf16_f32 v29, v29, v29
	v_add3_u32 v46, v38, v46, v27
	ds_write_b16 v46, v29 offset:12288
	v_fma_f32 v29, v50, v18, v215
	v_cvt_pk_bf16_f32 v29, v29, v29
	v_add3_u32 v46, v38, v199, v27
	ds_write_b16 v46, v29 offset:12544
	v_fma_f32 v29, v48, v18, v215
	v_cvt_pk_bf16_f32 v29, v29, v29
	v_add3_u32 v46, v38, v198, v27
	ds_write_b16 v46, v29 offset:12800
	v_mul_f32_e32 v29, v37, v18
	v_bfe_u32 v36, v29, 16, 1
	v_add3_u32 v29, v29, v36, s15
	v_add3_u32 v36, v38, v197, v27
	ds_write_b16_d16_hi v36, v29 offset:13056
	v_fma_f32 v29, v34, v18, v215
	v_cvt_pk_bf16_f32 v29, v29, v29
	v_add3_u32 v34, v38, v196, v27
	ds_write_b16 v34, v29 offset:13312
	v_sub_f32_e32 v29, v24, v39
	v_pk_fma_f32 v[24:25], v[40:41], s[22:23], v[24:25] op_sel_hi:[1,0,1] neg_lo:[1,0,0] neg_hi:[1,0,0]
	v_mul_f32_e32 v29, v29, v18
	v_mul_f32_e32 v24, v25, v18
	v_bfe_u32 v34, v29, 16, 1
	v_bfe_u32 v25, v24, 16, 1
	v_add3_u32 v29, v29, v34, s15
	v_add3_u32 v34, v38, v195, v27
	v_add3_u32 v24, v24, v25, s15
	v_add3_u32 v25, v38, v193, v27
	ds_write_b16_d16_hi v34, v29 offset:13568
	ds_write_b16_d16_hi v25, v24 offset:13824
	v_pk_fma_f32 v[24:25], v[40:41], s[22:23], v[32:33] op_sel_hi:[1,0,1] neg_lo:[1,0,0] neg_hi:[1,0,0]
	v_and_b32_e32 v167, 15, v43
	v_mul_f32_e32 v24, v25, v18
	v_bfe_u32 v25, v24, 16, 1
	v_add3_u32 v24, v24, v25, s15
	v_add3_u32 v25, v38, v191, v27
	ds_write_b16_d16_hi v25, v24 offset:14080
	v_fma_f32 v24, v28, v18, v215
	v_cvt_pk_bf16_f32 v24, v24, v24
	ds_write_b16 v35, v24 offset:14336
	v_sub_f32_e32 v24, v22, v39
	v_pk_fma_f32 v[22:23], v[40:41], s[22:23], v[22:23] op_sel_hi:[1,0,1] neg_lo:[1,0,0] neg_hi:[1,0,0]
	v_mul_f32_e32 v24, v24, v18
	v_mul_f32_e32 v22, v23, v18
	v_bfe_u32 v25, v24, 16, 1
	v_bfe_u32 v23, v22, 16, 1
	v_add3_u32 v24, v24, v25, s15
	v_add3_u32 v22, v22, v23, s15
	ds_write_b16_d16_hi v55, v24 offset:14592
	ds_write_b16_d16_hi v56, v22 offset:14848
	v_pk_fma_f32 v[22:23], v[40:41], s[22:23], v[30:31] op_sel_hi:[1,0,1] neg_lo:[1,0,0] neg_hi:[1,0,0]
	s_nop 0
	v_mul_f32_e32 v22, v23, v18
	v_bfe_u32 v23, v22, 16, 1
	v_add3_u32 v22, v22, v23, s15
	ds_write_b16_d16_hi v54, v22 offset:15104
	v_fma_f32 v22, v26, v18, v215
	v_cvt_pk_bf16_f32 v22, v22, v22
	ds_write_b16 v53, v22 offset:15360
	v_sub_f32_e32 v22, v20, v39
	v_pk_fma_f32 v[20:21], v[40:41], s[22:23], v[20:21] op_sel_hi:[1,0,1] neg_lo:[1,0,0] neg_hi:[1,0,0]
	v_mul_f32_e32 v22, v22, v18
	v_mul_f32_e32 v20, v21, v18
	v_mul_f32_e32 v18, v19, v18
	v_bfe_u32 v23, v22, 16, 1
	v_bfe_u32 v21, v20, 16, 1
	v_bfe_u32 v19, v18, 16, 1
	v_add3_u32 v22, v22, v23, s15
	v_add3_u32 v20, v20, v21, s15
	v_add3_u32 v18, v18, v19, s15
	ds_write_b16_d16_hi v51, v22 offset:15616
	ds_write_b16_d16_hi v49, v20 offset:15872
	ds_write_b16_d16_hi v45, v18 offset:16128
	v_lshrrev_b32_e32 v18, 1, v43
	v_and_b32_e32 v18, 32, v18
	v_lshl_or_b32 v166, v44, 6, v18
	v_or_b32_e32 v18, v166, v168
	v_lshl_add_u32 v165, v18, 8, 32
	v_bitop3_b32 v18, v42, v167, 1 bitop3:0x6c
	v_lshl_add_u32 v18, v18, 4, v165
	s_waitcnt lgkmcnt(0)
	s_barrier
	ds_read_b128 v[170:173], v18 offset:55296
	s_waitcnt lgkmcnt(0)
	v_mfma_f32_32x32x16_bf16 v[50:65], v[170:173], v[2:5], 0
	v_mfma_f32_32x32x16_bf16 v[34:49], v[170:173], v[6:9], 0
	v_mfma_f32_32x32x16_bf16 v[18:33], v[170:173], v[10:13], 0
	v_mfma_f32_32x32x16_bf16 v[2:17], v[170:173], v[14:17], 0
	v_bitop3_b32 v170, v169, v167, 2 bitop3:0x36
	v_lshl_add_u32 v170, v170, 4, v165
	ds_read_b128 v[170:173], v170 offset:55296
	s_waitcnt lgkmcnt(0)
	v_mfma_f32_32x32x16_bf16 v[50:65], v[170:173], v[138:141], v[50:65]
	v_bitop3_b32 v138, v169, v167, 4 bitop3:0x36
	v_lshl_add_u32 v138, v138, 4, v165
	ds_read_b128 v[138:141], v138 offset:55296
	v_mfma_f32_32x32x16_bf16 v[34:49], v[170:173], v[142:145], v[34:49]
	v_mfma_f32_32x32x16_bf16 v[18:33], v[170:173], v[146:149], v[18:33]
	s_waitcnt lgkmcnt(0)
	v_mfma_f32_32x32x16_bf16 v[34:49], v[138:141], v[126:129], v[34:49]
	v_bitop3_b32 v126, v169, v167, 6 bitop3:0x36
	v_lshl_add_u32 v126, v126, 4, v165
	ds_read_b128 v[126:129], v126 offset:55296
	v_mfma_f32_32x32x16_bf16 v[2:17], v[170:173], v[150:153], v[2:17]
	v_mfma_f32_32x32x16_bf16 v[18:33], v[138:141], v[130:133], v[18:33]
	s_waitcnt lgkmcnt(0)
	v_mfma_f32_32x32x16_bf16 v[34:49], v[126:129], v[114:117], v[34:49]
	v_bitop3_b32 v114, v169, v167, 8 bitop3:0x36
	v_lshl_add_u32 v114, v114, 4, v165
	ds_read_b128 v[114:117], v114 offset:55296
	v_mfma_f32_32x32x16_bf16 v[2:17], v[138:141], v[134:137], v[2:17]
	v_mfma_f32_32x32x16_bf16 v[18:33], v[126:129], v[118:121], v[18:33]
	v_mfma_f32_32x32x16_bf16 v[2:17], v[126:129], v[122:125], v[2:17]
	v_lshlrev_b32_e32 v128, 7, v164
	v_or_b32_e32 v126, v128, v168
	v_ashrrev_i32_e32 v127, 31, v126
	v_lshlrev_b64 v[130:131], 2, v[126:127]
	v_lshl_or_b32 v122, v169, 2, v166
	v_or_b32_e32 v124, s3, v168
	v_mov_b32_e32 v125, s5
	s_waitcnt lgkmcnt(0)
	v_mfma_f32_32x32x16_bf16 v[18:33], v[114:117], v[106:109], v[18:33]
	v_bitop3_b32 v106, v169, v167, 10 bitop3:0x36
	v_lshl_add_u32 v106, v106, 4, v165
	ds_read_b128 v[106:109], v106 offset:55296
	v_lshl_add_u64 v[132:133], s[6:7], 0, v[130:131]
	v_lshl_add_u64 v[130:131], s[92:93], 0, v[130:131]
	v_ashrrev_i32_e32 v123, 31, v122
	v_lshlrev_b64 v[122:123], 1, v[122:123]
	v_mfma_f32_32x32x16_bf16 v[2:17], v[114:117], v[110:113], v[2:17]
	s_add_i32 s3, s3, s18
	s_cmpk_gt_i32 s4, 0x7f
	s_waitcnt lgkmcnt(0)
	v_mfma_f32_32x32x16_bf16 v[18:33], v[106:109], v[98:101], v[18:33]
	v_bitop3_b32 v98, v169, v167, 12 bitop3:0x36
	v_lshl_add_u32 v98, v98, 4, v165
	ds_read_b128 v[98:101], v98 offset:55296
	v_mfma_f32_32x32x16_bf16 v[2:17], v[106:109], v[102:105], v[2:17]
	s_waitcnt lgkmcnt(0)
	v_mfma_f32_32x32x16_bf16 v[2:17], v[98:101], v[94:97], v[2:17]
	v_bitop3_b32 v94, v169, v167, 14 bitop3:0x36
	v_lshl_add_u32 v94, v94, 4, v165
	ds_read_b128 v[94:97], v94 offset:55296
	v_ashrrev_i32_e32 v167, 31, v166
	s_waitcnt lgkmcnt(0)
	v_mfma_f32_32x32x16_bf16 v[2:17], v[94:97], v[90:93], v[2:17]
	v_lshlrev_b64 v[90:91], 2, v[166:167]
	v_lshl_add_u64 v[92:93], s[10:11], 0, v[90:91]
	v_lshl_add_u64 v[90:91], s[40:41], 0, v[90:91]
	v_lshl_add_u64 v[92:93], v[92:93], 0, v[154:155]
	v_lshl_add_u64 v[94:95], v[90:91], 0, v[154:155]
	global_load_dwordx4 v[114:117], v[92:93], off
	global_load_dwordx4 v[118:121], v[94:95], off
	global_load_dwordx4 v[106:109], v[92:93], off offset:32
	global_load_dwordx4 v[110:113], v[94:95], off offset:32
	global_load_dwordx4 v[98:101], v[92:93], off offset:64
	global_load_dwordx4 v[102:105], v[94:95], off offset:64
	s_nop 0
	global_load_dwordx4 v[90:93], v[92:93], off offset:96
	s_nop 0
	global_load_dwordx4 v[94:97], v[94:95], off offset:96
	s_nop 0
	global_load_dword v142, v[132:133], off
	global_load_dword v143, v[132:133], off offset:128
	global_load_dword v144, v[132:133], off offset:256
	global_load_dword v145, v[132:133], off offset:384
	global_load_dword v146, v[130:131], off
	global_load_dword v147, v[130:131], off offset:128
	global_load_dword v148, v[130:131], off offset:256
	global_load_dword v149, v[130:131], off offset:384
	v_lshlrev_b64 v[134:135], 11, v[124:125]
	v_lshl_add_u64 v[134:135], s[62:63], 0, v[134:135]
	v_lshl_add_u64 v[134:135], v[134:135], 0, v[122:123]
	v_add_co_u32_e32 v136, vcc, 0x10000, v134
	s_nop 1
	v_addc_co_u32_e32 v137, vcc, 0, v135, vcc
	v_add_co_u32_e32 v138, vcc, 0x20000, v134
	s_nop 1
	v_addc_co_u32_e32 v139, vcc, 0, v135, vcc
	v_add_co_u32_e32 v140, vcc, 0x30000, v134
	s_nop 1
	v_addc_co_u32_e32 v141, vcc, 0, v135, vcc
	s_barrier
	v_and_b32_e32 v150, 31, v0
	v_lshlrev_b32_e32 v170, 6, v150
	v_bfe_u32 v151, v0, 5, 1
	v_lshl_add_u32 v170, v151, 3, v170
	v_lshrrev_b32_e32 v168, 6, v0
	v_lshl_add_u32 v170, v168, 13, v170
	v_add_u32_e32 v170, 0xd820, v170
	v_bfe_u32 v150, v0, 1, 2
	v_xor_b32_e32 v151, 0, v150
	v_lshl_add_u32 v152, v151, 4, v170
	v_xor_b32_e32 v151, 1, v150
	v_lshl_add_u32 v153, v151, 4, v170
	v_xor_b32_e32 v151, 2, v150
	v_lshl_add_u32 v164, v151, 4, v170
	v_xor_b32_e32 v151, 3, v150
	v_lshl_add_u32 v165, v151, 4, v170
	v_bfe_u32 v169, v0, 2, 4
	v_lshlrev_b32_e32 v166, 6, v169
	v_and_b32_e32 v151, 3, v0
	v_bfe_u32 v150, v0, 3, 2
	v_xor_b32_e32 v150, v151, v150
	v_lshl_add_u32 v166, v150, 4, v166
	v_lshl_add_u32 v166, v168, 13, v166
	v_add_u32_e32 v166, 0xd820, v166
	v_and_b32_e32 v167, -32, v124
	v_add_u32_e32 v167, v167, v169
	v_lshlrev_b32_e32 v167, 11, v167
	v_lshl_add_u32 v167, v168, 6, v167
	v_lshl_add_u32 v167, v151, 4, v167
	s_waitcnt vmcnt(0)
	s_nop 1
	v_permlane32_swap_b32 v216, v218
	v_permlane32_swap_b32 v217, v219
	v_permlane32_swap_b32 v220, v222
	v_permlane32_swap_b32 v221, v223
	v_permlane32_swap_b32 v224, v226
	v_permlane32_swap_b32 v225, v227
	v_permlane32_swap_b32 v228, v230
	v_permlane32_swap_b32 v229, v231
	v_permlane32_swap_b32 v232, v234
	v_permlane32_swap_b32 v233, v235
	v_permlane32_swap_b32 v236, v238
	v_permlane32_swap_b32 v237, v239
	v_permlane32_swap_b32 v252, v254
	v_permlane32_swap_b32 v253, v255
	v_mul_f32_e32 v150, v118, v142
	v_fmac_f32_e32 v150, v50, v114
	v_add_f32_e32 v50, v146, v150
	v_lshlrev_b32_e32 v151, 16, v216
	v_mul_f32_e32 v50, v50, v151
	v_mul_f32_e32 v150, v119, v142
	v_fmac_f32_e32 v150, v51, v115
	v_add_f32_e32 v51, v146, v150
	v_and_b32_e32 v151, 0xffff0000, v216
	v_mul_f32_e32 v51, v51, v151
	v_mul_f32_e32 v150, v120, v142
	v_fmac_f32_e32 v150, v52, v116
	v_add_f32_e32 v52, v146, v150
	v_lshlrev_b32_e32 v151, 16, v217
	v_mul_f32_e32 v52, v52, v151
	v_mul_f32_e32 v150, v121, v142
	v_fmac_f32_e32 v150, v53, v117
	v_add_f32_e32 v53, v146, v150
	v_and_b32_e32 v151, 0xffff0000, v217
	v_mul_f32_e32 v53, v53, v151
	v_cvt_pk_bf16_f32 v50, v50, v51
	v_cvt_pk_bf16_f32 v51, v52, v53
	ds_write_b64 v152, v[50:51] offset:0
	v_mul_f32_e32 v150, v110, v142
	v_fmac_f32_e32 v150, v54, v106
	v_add_f32_e32 v54, v146, v150
	v_lshlrev_b32_e32 v151, 16, v218
	v_mul_f32_e32 v54, v54, v151
	v_mul_f32_e32 v150, v111, v142
	v_fmac_f32_e32 v150, v55, v107
	v_add_f32_e32 v55, v146, v150
	v_and_b32_e32 v151, 0xffff0000, v218
	v_mul_f32_e32 v55, v55, v151
	v_mul_f32_e32 v150, v112, v142
	v_fmac_f32_e32 v150, v56, v108
	v_add_f32_e32 v56, v146, v150
	v_lshlrev_b32_e32 v151, 16, v219
	v_mul_f32_e32 v56, v56, v151
	v_mul_f32_e32 v150, v113, v142
	v_fmac_f32_e32 v150, v57, v109
	v_add_f32_e32 v57, v146, v150
	v_and_b32_e32 v151, 0xffff0000, v219
	v_mul_f32_e32 v57, v57, v151
	v_cvt_pk_bf16_f32 v54, v54, v55
	v_cvt_pk_bf16_f32 v55, v56, v57
	ds_write_b64 v153, v[54:55] offset:0
	v_mul_f32_e32 v150, v102, v142
	v_fmac_f32_e32 v150, v58, v98
	v_add_f32_e32 v58, v146, v150
	v_lshlrev_b32_e32 v151, 16, v220
	v_mul_f32_e32 v58, v58, v151
	v_mul_f32_e32 v150, v103, v142
	v_fmac_f32_e32 v150, v59, v99
	v_add_f32_e32 v59, v146, v150
	v_and_b32_e32 v151, 0xffff0000, v220
	v_mul_f32_e32 v59, v59, v151
	v_mul_f32_e32 v150, v104, v142
	v_fmac_f32_e32 v150, v60, v100
	v_add_f32_e32 v60, v146, v150
	v_lshlrev_b32_e32 v151, 16, v221
	v_mul_f32_e32 v60, v60, v151
	v_mul_f32_e32 v150, v105, v142
	v_fmac_f32_e32 v150, v61, v101
	v_add_f32_e32 v61, v146, v150
	v_and_b32_e32 v151, 0xffff0000, v221
	v_mul_f32_e32 v61, v61, v151
	v_cvt_pk_bf16_f32 v58, v58, v59
	v_cvt_pk_bf16_f32 v59, v60, v61
	ds_write_b64 v164, v[58:59] offset:0
	v_mul_f32_e32 v150, v94, v142
	v_fmac_f32_e32 v150, v62, v90
	v_add_f32_e32 v62, v146, v150
	v_lshlrev_b32_e32 v151, 16, v222
	v_mul_f32_e32 v62, v62, v151
	v_mul_f32_e32 v150, v95, v142
	v_fmac_f32_e32 v150, v63, v91
	v_add_f32_e32 v63, v146, v150
	v_and_b32_e32 v151, 0xffff0000, v222
	v_mul_f32_e32 v63, v63, v151
	v_mul_f32_e32 v150, v96, v142
	v_fmac_f32_e32 v150, v64, v92
	v_add_f32_e32 v64, v146, v150
	v_lshlrev_b32_e32 v151, 16, v223
	v_mul_f32_e32 v64, v64, v151
	v_mul_f32_e32 v150, v97, v142
	v_fmac_f32_e32 v150, v65, v93
	v_add_f32_e32 v65, v146, v150
	v_and_b32_e32 v151, 0xffff0000, v223
	v_mul_f32_e32 v65, v65, v151
	v_cvt_pk_bf16_f32 v62, v62, v63
	v_cvt_pk_bf16_f32 v63, v64, v65
	ds_write_b64 v165, v[62:63] offset:0
	v_mul_f32_e32 v150, v118, v143
	v_fmac_f32_e32 v150, v34, v114
	v_add_f32_e32 v34, v147, v150
	v_lshlrev_b32_e32 v151, 16, v224
	v_mul_f32_e32 v34, v34, v151
	v_mul_f32_e32 v150, v119, v143
	v_fmac_f32_e32 v150, v35, v115
	v_add_f32_e32 v35, v147, v150
	v_and_b32_e32 v151, 0xffff0000, v224
	v_mul_f32_e32 v35, v35, v151
	v_mul_f32_e32 v150, v120, v143
	v_fmac_f32_e32 v150, v36, v116
	v_add_f32_e32 v36, v147, v150
	v_lshlrev_b32_e32 v151, 16, v225
	v_mul_f32_e32 v36, v36, v151
	v_mul_f32_e32 v150, v121, v143
	v_fmac_f32_e32 v150, v37, v117
	v_add_f32_e32 v37, v147, v150
	v_and_b32_e32 v151, 0xffff0000, v225
	v_mul_f32_e32 v37, v37, v151
	v_cvt_pk_bf16_f32 v34, v34, v35
	v_cvt_pk_bf16_f32 v35, v36, v37
	ds_write_b64 v152, v[34:35] offset:2048
	v_mul_f32_e32 v150, v110, v143
	v_fmac_f32_e32 v150, v38, v106
	v_add_f32_e32 v38, v147, v150
	v_lshlrev_b32_e32 v151, 16, v226
	v_mul_f32_e32 v38, v38, v151
	v_mul_f32_e32 v150, v111, v143
	v_fmac_f32_e32 v150, v39, v107
	v_add_f32_e32 v39, v147, v150
	v_and_b32_e32 v151, 0xffff0000, v226
	v_mul_f32_e32 v39, v39, v151
	v_mul_f32_e32 v150, v112, v143
	v_fmac_f32_e32 v150, v40, v108
	v_add_f32_e32 v40, v147, v150
	v_lshlrev_b32_e32 v151, 16, v227
	v_mul_f32_e32 v40, v40, v151
	v_mul_f32_e32 v150, v113, v143
	v_fmac_f32_e32 v150, v41, v109
	v_add_f32_e32 v41, v147, v150
	v_and_b32_e32 v151, 0xffff0000, v227
	v_mul_f32_e32 v41, v41, v151
	v_cvt_pk_bf16_f32 v38, v38, v39
	v_cvt_pk_bf16_f32 v39, v40, v41
	ds_write_b64 v153, v[38:39] offset:2048
	v_mul_f32_e32 v150, v102, v143
	v_fmac_f32_e32 v150, v42, v98
	v_add_f32_e32 v42, v147, v150
	v_lshlrev_b32_e32 v151, 16, v228
	v_mul_f32_e32 v42, v42, v151
	v_mul_f32_e32 v150, v103, v143
	v_fmac_f32_e32 v150, v43, v99
	v_add_f32_e32 v43, v147, v150
	v_and_b32_e32 v151, 0xffff0000, v228
	v_mul_f32_e32 v43, v43, v151
	v_mul_f32_e32 v150, v104, v143
	v_fmac_f32_e32 v150, v44, v100
	v_add_f32_e32 v44, v147, v150
	v_lshlrev_b32_e32 v151, 16, v229
	v_mul_f32_e32 v44, v44, v151
	v_mul_f32_e32 v150, v105, v143
	v_fmac_f32_e32 v150, v45, v101
	v_add_f32_e32 v45, v147, v150
	v_and_b32_e32 v151, 0xffff0000, v229
	v_mul_f32_e32 v45, v45, v151
	v_cvt_pk_bf16_f32 v42, v42, v43
	v_cvt_pk_bf16_f32 v43, v44, v45
	ds_write_b64 v164, v[42:43] offset:2048
	v_mul_f32_e32 v150, v94, v143
	v_fmac_f32_e32 v150, v46, v90
	v_add_f32_e32 v46, v147, v150
	v_lshlrev_b32_e32 v151, 16, v230
	v_mul_f32_e32 v46, v46, v151
	v_mul_f32_e32 v150, v95, v143
	v_fmac_f32_e32 v150, v47, v91
	v_add_f32_e32 v47, v147, v150
	v_and_b32_e32 v151, 0xffff0000, v230
	v_mul_f32_e32 v47, v47, v151
	v_mul_f32_e32 v150, v96, v143
	v_fmac_f32_e32 v150, v48, v92
	v_add_f32_e32 v48, v147, v150
	v_lshlrev_b32_e32 v151, 16, v231
	v_mul_f32_e32 v48, v48, v151
	v_mul_f32_e32 v150, v97, v143
	v_fmac_f32_e32 v150, v49, v93
	v_add_f32_e32 v49, v147, v150
	v_and_b32_e32 v151, 0xffff0000, v231
	v_mul_f32_e32 v49, v49, v151
	v_cvt_pk_bf16_f32 v46, v46, v47
	v_cvt_pk_bf16_f32 v47, v48, v49
	ds_write_b64 v165, v[46:47] offset:2048
	v_mul_f32_e32 v150, v118, v144
	v_fmac_f32_e32 v150, v18, v114
	v_add_f32_e32 v18, v148, v150
	v_lshlrev_b32_e32 v151, 16, v232
	v_mul_f32_e32 v18, v18, v151
	v_mul_f32_e32 v150, v119, v144
	v_fmac_f32_e32 v150, v19, v115
	v_add_f32_e32 v19, v148, v150
	v_and_b32_e32 v151, 0xffff0000, v232
	v_mul_f32_e32 v19, v19, v151
	v_mul_f32_e32 v150, v120, v144
	v_fmac_f32_e32 v150, v20, v116
	v_add_f32_e32 v20, v148, v150
	v_lshlrev_b32_e32 v151, 16, v233
	v_mul_f32_e32 v20, v20, v151
	v_mul_f32_e32 v150, v121, v144
	v_fmac_f32_e32 v150, v21, v117
	v_add_f32_e32 v21, v148, v150
	v_and_b32_e32 v151, 0xffff0000, v233
	v_mul_f32_e32 v21, v21, v151
	v_cvt_pk_bf16_f32 v18, v18, v19
	v_cvt_pk_bf16_f32 v19, v20, v21
	ds_write_b64 v152, v[18:19] offset:4096
	v_mul_f32_e32 v150, v110, v144
	v_fmac_f32_e32 v150, v22, v106
	v_add_f32_e32 v22, v148, v150
	v_lshlrev_b32_e32 v151, 16, v234
	v_mul_f32_e32 v22, v22, v151
	v_mul_f32_e32 v150, v111, v144
	v_fmac_f32_e32 v150, v23, v107
	v_add_f32_e32 v23, v148, v150
	v_and_b32_e32 v151, 0xffff0000, v234
	v_mul_f32_e32 v23, v23, v151
	v_mul_f32_e32 v150, v112, v144
	v_fmac_f32_e32 v150, v24, v108
	v_add_f32_e32 v24, v148, v150
	v_lshlrev_b32_e32 v151, 16, v235
	v_mul_f32_e32 v24, v24, v151
	v_mul_f32_e32 v150, v113, v144
	v_fmac_f32_e32 v150, v25, v109
	v_add_f32_e32 v25, v148, v150
	v_and_b32_e32 v151, 0xffff0000, v235
	v_mul_f32_e32 v25, v25, v151
	v_cvt_pk_bf16_f32 v22, v22, v23
	v_cvt_pk_bf16_f32 v23, v24, v25
	ds_write_b64 v153, v[22:23] offset:4096
	v_mul_f32_e32 v150, v102, v144
	v_fmac_f32_e32 v150, v26, v98
	v_add_f32_e32 v26, v148, v150
	v_lshlrev_b32_e32 v151, 16, v236
	v_mul_f32_e32 v26, v26, v151
	v_mul_f32_e32 v150, v103, v144
	v_fmac_f32_e32 v150, v27, v99
	v_add_f32_e32 v27, v148, v150
	v_and_b32_e32 v151, 0xffff0000, v236
	v_mul_f32_e32 v27, v27, v151
	v_mul_f32_e32 v150, v104, v144
	v_fmac_f32_e32 v150, v28, v100
	v_add_f32_e32 v28, v148, v150
	v_lshlrev_b32_e32 v151, 16, v237
	v_mul_f32_e32 v28, v28, v151
	v_mul_f32_e32 v150, v105, v144
	v_fmac_f32_e32 v150, v29, v101
	v_add_f32_e32 v29, v148, v150
	v_and_b32_e32 v151, 0xffff0000, v237
	v_mul_f32_e32 v29, v29, v151
	v_cvt_pk_bf16_f32 v26, v26, v27
	v_cvt_pk_bf16_f32 v27, v28, v29
	ds_write_b64 v164, v[26:27] offset:4096
	v_mul_f32_e32 v150, v94, v144
	v_fmac_f32_e32 v150, v30, v90
	v_add_f32_e32 v30, v148, v150
	v_lshlrev_b32_e32 v151, 16, v238
	v_mul_f32_e32 v30, v30, v151
	v_mul_f32_e32 v150, v95, v144
	v_fmac_f32_e32 v150, v31, v91
	v_add_f32_e32 v31, v148, v150
	v_and_b32_e32 v151, 0xffff0000, v238
	v_mul_f32_e32 v31, v31, v151
	v_mul_f32_e32 v150, v96, v144
	v_fmac_f32_e32 v150, v32, v92
	v_add_f32_e32 v32, v148, v150
	v_lshlrev_b32_e32 v151, 16, v239
	v_mul_f32_e32 v32, v32, v151
	v_mul_f32_e32 v150, v97, v144
	v_fmac_f32_e32 v150, v33, v93
	v_add_f32_e32 v33, v148, v150
	v_and_b32_e32 v151, 0xffff0000, v239
	v_mul_f32_e32 v33, v33, v151
	v_cvt_pk_bf16_f32 v30, v30, v31
	v_cvt_pk_bf16_f32 v31, v32, v33
	ds_write_b64 v165, v[30:31] offset:4096
	v_mul_f32_e32 v150, v118, v145
	v_fmac_f32_e32 v150, v2, v114
	v_add_f32_e32 v2, v149, v150
	v_lshlrev_b32_e32 v151, 16, v252
	v_mul_f32_e32 v2, v2, v151
	v_mul_f32_e32 v150, v119, v145
	v_fmac_f32_e32 v150, v3, v115
	v_add_f32_e32 v3, v149, v150
	v_and_b32_e32 v151, 0xffff0000, v252
	v_mul_f32_e32 v3, v3, v151
	v_mul_f32_e32 v150, v120, v145
	v_fmac_f32_e32 v150, v4, v116
	v_add_f32_e32 v4, v149, v150
	v_lshlrev_b32_e32 v151, 16, v253
	v_mul_f32_e32 v4, v4, v151
	v_mul_f32_e32 v150, v121, v145
	v_fmac_f32_e32 v150, v5, v117
	v_add_f32_e32 v5, v149, v150
	v_and_b32_e32 v151, 0xffff0000, v253
	v_mul_f32_e32 v5, v5, v151
	v_cvt_pk_bf16_f32 v2, v2, v3
	v_cvt_pk_bf16_f32 v3, v4, v5
	ds_write_b64 v152, v[2:3] offset:6144
	v_mul_f32_e32 v150, v110, v145
	v_fmac_f32_e32 v150, v6, v106
	v_add_f32_e32 v6, v149, v150
	v_lshlrev_b32_e32 v151, 16, v254
	v_mul_f32_e32 v6, v6, v151
	v_mul_f32_e32 v150, v111, v145
	v_fmac_f32_e32 v150, v7, v107
	v_add_f32_e32 v7, v149, v150
	v_and_b32_e32 v151, 0xffff0000, v254
	v_mul_f32_e32 v7, v7, v151
	v_mul_f32_e32 v150, v112, v145
	v_fmac_f32_e32 v150, v8, v108
	v_add_f32_e32 v8, v149, v150
	v_lshlrev_b32_e32 v151, 16, v255
	v_mul_f32_e32 v8, v8, v151
	v_mul_f32_e32 v150, v113, v145
	v_fmac_f32_e32 v150, v9, v109
	v_add_f32_e32 v9, v149, v150
	v_and_b32_e32 v151, 0xffff0000, v255
	v_mul_f32_e32 v9, v9, v151
	v_cvt_pk_bf16_f32 v6, v6, v7
	v_cvt_pk_bf16_f32 v7, v8, v9
	ds_write_b64 v153, v[6:7] offset:6144
	v_mul_f32_e32 v150, v102, v145
	v_fmac_f32_e32 v150, v10, v98
	v_add_f32_e32 v10, v149, v150
	v_lshlrev_b32_e32 v151, 16, v240
	v_mul_f32_e32 v10, v10, v151
	v_mul_f32_e32 v150, v103, v145
	v_fmac_f32_e32 v150, v11, v99
	v_add_f32_e32 v11, v149, v150
	v_and_b32_e32 v151, 0xffff0000, v240
	v_mul_f32_e32 v11, v11, v151
	v_mul_f32_e32 v150, v104, v145
	v_fmac_f32_e32 v150, v12, v100
	v_add_f32_e32 v12, v149, v150
	v_lshlrev_b32_e32 v151, 16, v241
	v_mul_f32_e32 v12, v12, v151
	v_mul_f32_e32 v150, v105, v145
	v_fmac_f32_e32 v150, v13, v101
	v_add_f32_e32 v13, v149, v150
	v_and_b32_e32 v151, 0xffff0000, v241
	v_mul_f32_e32 v13, v13, v151
	v_cvt_pk_bf16_f32 v10, v10, v11
	v_cvt_pk_bf16_f32 v11, v12, v13
	ds_write_b64 v164, v[10:11] offset:6144
	v_mul_f32_e32 v150, v94, v145
	v_fmac_f32_e32 v150, v14, v90
	v_add_f32_e32 v14, v149, v150
	v_lshlrev_b32_e32 v151, 16, v246
	v_mul_f32_e32 v14, v14, v151
	v_mul_f32_e32 v150, v95, v145
	v_fmac_f32_e32 v150, v15, v91
	v_add_f32_e32 v15, v149, v150
	v_and_b32_e32 v151, 0xffff0000, v246
	v_mul_f32_e32 v15, v15, v151
	v_mul_f32_e32 v150, v96, v145
	v_fmac_f32_e32 v150, v16, v92
	v_add_f32_e32 v16, v149, v150
	v_lshlrev_b32_e32 v151, 16, v247
	v_mul_f32_e32 v16, v16, v151
	v_mul_f32_e32 v150, v97, v145
	v_fmac_f32_e32 v150, v17, v93
	v_add_f32_e32 v17, v149, v150
	v_and_b32_e32 v151, 0xffff0000, v247
	v_mul_f32_e32 v17, v17, v151
	v_cvt_pk_bf16_f32 v14, v14, v15
	v_cvt_pk_bf16_f32 v15, v16, v17
	ds_write_b64 v165, v[14:15] offset:6144
	s_waitcnt lgkmcnt(0)
	ds_read_b128 v[2:5], v166 offset:0
	ds_read_b128 v[6:9], v166 offset:1024
	ds_read_b128 v[10:13], v166 offset:2048
	ds_read_b128 v[14:17], v166 offset:3072
	ds_read_b128 v[18:21], v166 offset:4096
	ds_read_b128 v[22:25], v166 offset:5120
	ds_read_b128 v[26:29], v166 offset:6144
	ds_read_b128 v[30:33], v166 offset:7168
	s_waitcnt lgkmcnt(7)
	global_store_dwordx4 v167, v[2:5], s[62:63] offset:1536
	v_add_u32_e32 v151, 0x8000, v167
	s_waitcnt lgkmcnt(6)
	global_store_dwordx4 v151, v[6:9], s[62:63] offset:1536
	v_add_u32_e32 v150, 0x10000, v167
	s_waitcnt lgkmcnt(5)
	global_store_dwordx4 v150, v[10:13], s[62:63] offset:1536
	v_add_u32_e32 v151, 0x18000, v167
	s_waitcnt lgkmcnt(4)
	global_store_dwordx4 v151, v[14:17], s[62:63] offset:1536
	v_add_u32_e32 v150, 0x20000, v167
	s_waitcnt lgkmcnt(3)
	global_store_dwordx4 v150, v[18:21], s[62:63] offset:1536
	v_add_u32_e32 v151, 0x28000, v167
	s_waitcnt lgkmcnt(2)
	global_store_dwordx4 v151, v[22:25], s[62:63] offset:1536
	v_add_u32_e32 v150, 0x30000, v167
	s_waitcnt lgkmcnt(1)
	global_store_dwordx4 v150, v[26:29], s[62:63] offset:1536
	v_add_u32_e32 v151, 0x38000, v167
	s_waitcnt lgkmcnt(0)
	global_store_dwordx4 v151, v[30:33], s[62:63] offset:1536
	s_barrier
	s_cbranch_scc0 .LBB0_779

.LBB0_849:
	v_mov_b32_e32 v43, v0
	s_ashr_i32 s5, s3, 31
	v_ashrrev_i32_e32 v44, 7, v43
	s_waitcnt vmcnt(7)
	v_add_u32_e32 v130, s2, v44
	v_ashrrev_i32_e32 v131, 31, v130
	v_and_b32_e32 v134, 31, v43
	s_waitcnt vmcnt(0)
	v_lshlrev_b64 v[2:3], 15, v[130:131]
	v_bfe_u32 v135, v43, 5, 1
	v_lshl_add_u64 v[2:3], s[56:57], 0, v[2:3]
	v_and_b32_e32 v18, 63, v43
	v_lshlrev_b32_e32 v18, 4, v18
	v_lshlrev_b32_e32 v154, 4, v135
	v_add_u32_e32 v18, 0x1000, v18
	v_add_co_u32_e32 v18, vcc, v2, v18
	s_nop 1
	v_addc_co_u32_e32 v19, vcc, 0, v3, vcc
	v_add_co_u32_e32 v20, vcc, s14, v18
	v_ashrrev_i32_e32 v45, 2, v43
	s_nop 0
	v_addc_co_u32_e32 v21, vcc, 0, v19, vcc
	v_add_co_u32_e32 v22, vcc, s17, v18
	global_load_dwordx4 v[2:5], v[18:19], off offset:-4096
	global_load_dwordx4 v[6:9], v[20:21], off offset:-4096
	v_addc_co_u32_e32 v23, vcc, 0, v19, vcc
	v_add_co_u32_e32 v24, vcc, s30, v18
	global_load_dwordx4 v[10:13], v[22:23], off offset:-4096
	s_nop 0
	v_addc_co_u32_e32 v25, vcc, 0, v19, vcc
	global_load_dwordx4 v[14:17], v[24:25], off offset:-4096
	global_load_dwordx4 v[114:117], v[18:19], off offset:-3072
	global_load_dwordx4 v[118:121], v[20:21], off offset:-3072
	global_load_dwordx4 v[122:125], v[22:23], off offset:-3072
	global_load_dwordx4 v[126:129], v[24:25], off offset:-3072
	global_load_dwordx4 v[102:105], v[20:21], off offset:-2048
	global_load_dwordx4 v[106:109], v[22:23], off offset:-2048
	global_load_dwordx4 v[110:113], v[24:25], off offset:-2048
	global_load_dwordx4 v[90:93], v[20:21], off offset:-1024
	global_load_dwordx4 v[94:97], v[22:23], off offset:-1024
	global_load_dwordx4 v[98:101], v[24:25], off offset:-1024
	global_load_dwordx4 v[82:85], v[22:23], off
	global_load_dwordx4 v[86:89], v[24:25], off
	global_load_dwordx4 v[74:77], v[22:23], off offset:1024
	global_load_dwordx4 v[78:81], v[24:25], off offset:1024
	global_load_dwordx4 v[70:73], v[24:25], off offset:2048
	global_load_dwordx4 v[66:69], v[24:25], off offset:3072
	v_add_u32_e32 v18, s3, v45
	v_ashrrev_i32_e32 v19, 31, v18
	v_lshlrev_b32_e32 v20, 6, v43
	v_lshlrev_b64 v[18:19], 12, v[18:19]
	v_and_b32_e32 v46, 0xc0, v20
	v_lshl_add_u64 v[18:19], s[60:61], 0, v[18:19]
	v_lshlrev_b32_e32 v20, 1, v46
	v_mov_b32_e32 v21, v155
	v_lshl_add_u64 v[34:35], v[18:19], 0, v[20:21]
	global_load_dwordx4 v[18:21], v[34:35], off offset:3632
	global_load_dwordx4 v[22:25], v[34:35], off offset:3616
	global_load_dwordx4 v[26:29], v[34:35], off offset:3600
	global_load_dwordx4 v[30:33], v[34:35], off offset:3584
	global_load_dwordx4 v[36:39], v[34:35], off offset:3680
	global_load_dwordx4 v[176:179], v[34:35], off offset:3664
	global_load_dwordx4 v[48:51], v[34:35], off offset:3648
	global_load_dwordx4 v[182:185], v[34:35], off offset:3696
	v_and_b32_e32 v215, 31, v0
	v_add_u32_e32 v215, s3, v215
	v_lshlrev_b32_e32 v215, 12, v215
	v_and_b32_e32 v245, 0x1c0, v0
	v_add_u32_e32 v215, v215, v245
	v_bfe_u32 v245, v0, 5, 1
	v_lshl_add_u32 v245, v245, 3, v215
	v_bfe_u32 v215, v0, 5, 1
	v_lshl_add_u32 v215, v215, 3, v245
	global_load_dwordx4 v[216:219], v215, s[60:61] offset:3072
	global_load_dwordx4 v[220:223], v215, s[60:61] offset:3104
	s_add_u32 s98, s60, 0x20000
	s_addc_u32 s99, s61, 0
	global_load_dwordx4 v[224:227], v215, s[98:99] offset:3072
	global_load_dwordx4 v[228:231], v215, s[98:99] offset:3104
	s_add_u32 s100, s60, 0x40000
	s_addc_u32 s101, s61, 0
	global_load_dwordx4 v[232:235], v215, s[100:101] offset:3072
	global_load_dwordx4 v[236:239], v215, s[100:101] offset:3104
	s_add_u32 s98, s60, 0x60000
	s_addc_u32 s99, s61, 0
	global_load_dwordx4 v[252:255], v215, s[98:99] offset:3072
	global_load_dwordx2 v[240:241], v245, s[98:99] offset:3104
	global_load_dwordx2 v[246:247], v245, s[98:99] offset:3120
	v_lshrrev_b32_e32 v42, 5, v43
	s_add_i32 s4, s4, s46
	s_waitcnt vmcnt(16)
	v_lshlrev_b32_e32 v144, 16, v18
	s_waitcnt vmcnt(15)
	v_lshlrev_b32_e32 v150, 16, v22
	s_waitcnt vmcnt(14)
	v_lshlrev_b32_e32 v168, 16, v26
	s_waitcnt vmcnt(13)
	v_lshlrev_b32_e32 v174, 16, v30
	v_and_b32_e32 v173, 0xffff0000, v30
	v_add_f32_e32 v30, 0, v174
	v_lshlrev_b32_e32 v172, 16, v31
	v_add_f32_e32 v30, v30, v173
	v_and_b32_e32 v171, 0xffff0000, v31
	v_mul_f32_e32 v31, v173, v173
	v_add_f32_e32 v30, v30, v172
	v_lshlrev_b32_e32 v170, 16, v32
	v_fmac_f32_e32 v31, v174, v174
	v_add_f32_e32 v30, v30, v171
	v_and_b32_e32 v169, 0xffff0000, v32
	v_fmac_f32_e32 v31, v172, v172
	v_add_f32_e32 v30, v30, v170
	v_lshlrev_b32_e32 v167, 16, v33
	v_fmac_f32_e32 v31, v171, v171
	v_add_f32_e32 v30, v30, v169
	v_and_b32_e32 v165, 0xffff0000, v33
	v_fmac_f32_e32 v31, v170, v170
	v_add_f32_e32 v30, v30, v167
	v_fmac_f32_e32 v31, v169, v169
	v_add_f32_e32 v30, v30, v165
	v_fmac_f32_e32 v31, v167, v167
	v_and_b32_e32 v166, 0xffff0000, v26
	v_add_f32_e32 v26, v30, v168
	v_fmac_f32_e32 v31, v165, v165
	v_lshlrev_b32_e32 v164, 16, v27
	v_add_f32_e32 v26, v26, v166
	v_and_b32_e32 v153, 0xffff0000, v27
	v_fmac_f32_e32 v31, v168, v168
	v_add_f32_e32 v26, v26, v164
	v_lshlrev_b32_e32 v152, 16, v28
	v_fmac_f32_e32 v31, v166, v166
	v_add_f32_e32 v26, v26, v153
	v_and_b32_e32 v151, 0xffff0000, v28
	v_fmac_f32_e32 v31, v164, v164
	v_add_f32_e32 v26, v26, v152
	v_lshlrev_b32_e32 v148, 16, v29
	v_fmac_f32_e32 v31, v153, v153
	v_add_f32_e32 v26, v26, v151
	v_and_b32_e32 v146, 0xffff0000, v29
	v_fmac_f32_e32 v31, v152, v152
	v_add_f32_e32 v26, v26, v148
	v_fmac_f32_e32 v31, v151, v151
	v_add_f32_e32 v26, v26, v146
	v_fmac_f32_e32 v31, v148, v148
	v_and_b32_e32 v149, 0xffff0000, v22
	v_add_f32_e32 v22, v26, v150
	v_fmac_f32_e32 v31, v146, v146
	v_lshlrev_b32_e32 v147, 16, v23
	v_add_f32_e32 v22, v22, v149
	v_and_b32_e32 v145, 0xffff0000, v23
	v_fmac_f32_e32 v31, v150, v150
	v_add_f32_e32 v22, v22, v147
	v_lshlrev_b32_e32 v143, 16, v24
	v_fmac_f32_e32 v31, v149, v149
	v_add_f32_e32 v22, v22, v145
	v_and_b32_e32 v141, 0xffff0000, v24
	v_fmac_f32_e32 v31, v147, v147
	v_add_f32_e32 v22, v22, v143
	v_lshlrev_b32_e32 v139, 16, v25
	v_fmac_f32_e32 v31, v145, v145
	v_add_f32_e32 v22, v22, v141
	v_and_b32_e32 v137, 0xffff0000, v25
	v_fmac_f32_e32 v31, v143, v143
	v_add_f32_e32 v22, v22, v139
	v_fmac_f32_e32 v31, v141, v141
	v_add_f32_e32 v22, v22, v137
	v_fmac_f32_e32 v31, v139, v139
	v_and_b32_e32 v142, 0xffff0000, v18
	v_add_f32_e32 v18, v22, v144
	v_fmac_f32_e32 v31, v137, v137
	v_lshlrev_b32_e32 v140, 16, v19
	v_add_f32_e32 v18, v18, v142
	v_and_b32_e32 v138, 0xffff0000, v19
	v_fmac_f32_e32 v31, v144, v144
	v_add_f32_e32 v18, v18, v140
	v_lshlrev_b32_e32 v133, 16, v20
	v_fmac_f32_e32 v31, v142, v142
	v_add_f32_e32 v18, v18, v138
	v_and_b32_e32 v131, 0xffff0000, v20
	v_fmac_f32_e32 v31, v140, v140
	v_add_f32_e32 v18, v18, v133
	v_lshlrev_b32_e32 v64, 16, v21
	v_fmac_f32_e32 v31, v138, v138
	v_add_f32_e32 v18, v18, v131
	v_and_b32_e32 v62, 0xffff0000, v21
	v_fmac_f32_e32 v31, v133, v133
	v_add_f32_e32 v18, v18, v64
	v_fmac_f32_e32 v31, v131, v131
	v_add_f32_e32 v18, v18, v62
	s_waitcnt vmcnt(10)
	v_lshlrev_b32_e32 v136, 16, v48
	v_fmac_f32_e32 v31, v64, v64
	v_and_b32_e32 v132, 0xffff0000, v48
	v_add_f32_e32 v18, v18, v136
	v_fmac_f32_e32 v31, v62, v62
	v_lshlrev_b32_e32 v65, 16, v49
	v_add_f32_e32 v18, v18, v132
	v_and_b32_e32 v63, 0xffff0000, v49
	v_fmac_f32_e32 v31, v136, v136
	v_add_f32_e32 v18, v18, v65
	v_lshlrev_b32_e32 v60, 16, v50
	v_fmac_f32_e32 v31, v132, v132
	v_add_f32_e32 v18, v18, v63
	v_and_b32_e32 v59, 0xffff0000, v50
	v_fmac_f32_e32 v31, v65, v65
	v_add_f32_e32 v18, v18, v60
	v_lshlrev_b32_e32 v57, 16, v51
	v_fmac_f32_e32 v31, v63, v63
	v_add_f32_e32 v18, v18, v59
	v_and_b32_e32 v55, 0xffff0000, v51
	v_fmac_f32_e32 v31, v60, v60
	v_add_f32_e32 v18, v18, v57
	v_fmac_f32_e32 v31, v59, v59
	v_add_f32_e32 v18, v18, v55
	v_lshlrev_b32_e32 v61, 16, v176
	v_fmac_f32_e32 v31, v57, v57
	v_and_b32_e32 v58, 0xffff0000, v176
	v_add_f32_e32 v18, v18, v61
	v_fmac_f32_e32 v31, v55, v55
	v_lshlrev_b32_e32 v56, 16, v177
	v_add_f32_e32 v18, v18, v58
	v_and_b32_e32 v54, 0xffff0000, v177
	v_fmac_f32_e32 v31, v61, v61
	v_add_f32_e32 v18, v18, v56
	v_lshlrev_b32_e32 v53, 16, v178
	v_fmac_f32_e32 v31, v58, v58
	v_add_f32_e32 v18, v18, v54
	v_and_b32_e32 v51, 0xffff0000, v178
	v_fmac_f32_e32 v31, v56, v56
	v_add_f32_e32 v18, v18, v53
	v_lshlrev_b32_e32 v49, 16, v179
	v_fmac_f32_e32 v31, v54, v54
	v_add_f32_e32 v18, v18, v51
	v_and_b32_e32 v47, 0xffff0000, v179
	v_fmac_f32_e32 v31, v53, v53
	v_add_f32_e32 v18, v18, v49
	v_fmac_f32_e32 v31, v51, v51
	v_add_f32_e32 v18, v18, v47
	v_lshlrev_b32_e32 v52, 16, v36
	v_fmac_f32_e32 v31, v49, v49
	v_and_b32_e32 v50, 0xffff0000, v36
	v_add_f32_e32 v18, v18, v52
	v_fmac_f32_e32 v31, v47, v47
	v_lshlrev_b32_e32 v48, 16, v37
	v_add_f32_e32 v18, v18, v50
	v_fmac_f32_e32 v31, v52, v52
	v_add_f32_e32 v18, v18, v48
	v_and_b32_e32 v37, 0xffff0000, v37
	v_fmac_f32_e32 v31, v50, v50
	v_lshlrev_b32_e32 v34, 16, v38
	v_mov_b32_e32 v35, v37
	v_add_f32_e32 v20, v18, v37
	v_fmac_f32_e32 v31, v48, v48
	v_and_b32_e32 v24, 0xffff0000, v38
	v_pk_mul_f32 v[18:19], v[34:35], v[34:35]
	v_add_f32_e32 v20, v20, v34
	v_lshlrev_b32_e32 v25, 16, v39
	v_add_f32_e32 v19, v19, v31
	v_add_f32_e32 v20, v20, v24
	v_add_f32_e32 v21, v18, v19
	v_pk_mul_f32 v[18:19], v[24:25], v[24:25]
	v_add_f32_e32 v20, v20, v25
	v_and_b32_e32 v33, 0xffff0000, v39
	v_add_f32_e32 v18, v18, v21
	s_waitcnt vmcnt(9)
	v_lshlrev_b32_e32 v28, 16, v182
	v_mov_b32_e32 v29, v33
	v_add_f32_e32 v20, v20, v33
	v_add_f32_e32 v21, v19, v18
	v_and_b32_e32 v22, 0xffff0000, v182
	v_pk_mul_f32 v[18:19], v[28:29], v[28:29]
	v_add_f32_e32 v20, v20, v28
	v_lshlrev_b32_e32 v23, 16, v183
	v_add_f32_e32 v19, v19, v21
	v_add_f32_e32 v20, v20, v22
	v_add_f32_e32 v21, v18, v19
	v_pk_mul_f32 v[18:19], v[22:23], v[22:23]
	v_add_f32_e32 v29, v20, v23
	v_and_b32_e32 v31, 0xffff0000, v183
	v_add_f32_e32 v18, v18, v21
	v_lshlrev_b32_e32 v26, 16, v184
	v_mov_b32_e32 v27, v31
	v_add_f32_e32 v29, v29, v31
	v_and_b32_e32 v36, s0, v38
	v_add_f32_e32 v18, v19, v18
	v_and_b32_e32 v20, 0xffff0000, v184
	v_pk_mul_f32 v[38:39], v[26:27], v[26:27]
	v_add_f32_e32 v27, v29, v26
	v_lshlrev_b32_e32 v21, 16, v185
	v_add_f32_e32 v18, v39, v18
	v_add_f32_e32 v27, v27, v20
	v_and_b32_e32 v29, 64, v181
	v_add_f32_e32 v18, v38, v18
	v_pk_mul_f32 v[40:41], v[20:21], v[20:21]
	v_add_f32_e32 v39, v27, v21
	v_xor_b32_e32 v27, 1, v181
	v_add_u32_e32 v29, 64, v29
	v_and_b32_e32 v19, 0xffff0000, v185
	v_add_f32_e32 v18, v40, v18
	v_cmp_lt_i32_e32 vcc, v27, v29
	v_add_f32_e32 v18, v41, v18
	v_mul_f32_e32 v38, v19, v19
	v_cndmask_b32_e32 v27, v181, v27, vcc
	v_lshlrev_b32_e32 v27, 2, v27
	v_pk_add_f32 v[38:39], v[38:39], v[18:19]
	ds_bpermute_b32 v41, v27, v39
	ds_bpermute_b32 v40, v27, v38
	v_xor_b32_e32 v35, 2, v181
	v_cmp_lt_i32_e32 vcc, v35, v29
	v_and_b32_e32 v30, s0, v182
	v_mov_b32_e32 v32, v36
	v_cndmask_b32_e32 v29, v181, v35, vcc
	v_lshlrev_b32_e32 v29, 2, v29
	s_waitcnt lgkmcnt(0)
	v_pk_add_f32 v[38:39], v[38:39], v[40:41]
	ds_bpermute_b32 v41, v29, v39
	ds_bpermute_b32 v40, v29, v38
	s_waitcnt lgkmcnt(0)
	v_pk_add_f32 v[40:41], v[38:39], v[40:41]
	s_nop 0
	v_pk_mul_f32 v[38:39], v[40:41], s[22:23] op_sel_hi:[1,0]
	v_pk_fma_f32 v[36:37], v[40:41], s[22:23], v[36:37] op_sel_hi:[1,0,1] neg_lo:[1,0,0] neg_hi:[1,0,0]
	v_fma_f32 v18, -v39, v39, v38
	v_max_f32_e32 v18, 0, v18
	v_add_f32_e32 v18, 0x358637bd, v18
	v_cmp_gt_f32_e32 vcc, s33, v18
	v_mul_f32_e32 v27, 0x4b800000, v18
	v_sub_f32_e32 v29, v174, v39
	v_cndmask_b32_e32 v18, v18, v27, vcc
	v_rsq_f32_e32 v18, v18
	v_sub_f32_e32 v19, v19, v39
	v_mul_f32_e32 v27, 0x45800000, v18
	v_cndmask_b32_e32 v18, v18, v27, vcc
	v_mul_f32_e32 v29, v29, v18
	v_lshlrev_b32_e32 v27, 1, v45
	v_bfe_u32 v35, v29, 16, 1
	v_ashrrev_i32_e32 v45, 1, v43
	v_and_b32_e32 v27, 14, v27
	v_add3_u32 v29, v29, v35, s15
	v_lshl_add_u32 v35, v46, 8, 32
	v_and_b32_e32 v46, -16, v45
	v_add3_u32 v174, v35, v46, v27
	ds_write_b16_d16_hi v174, v29 offset:55296
	v_mul_f32_e64 v215, -v39, v18
	v_fma_f32 v29, v173, v18, v215
	v_cvt_pk_bf16_f32 v29, v29, v29
	v_bitop3_b32 v173, v45, 16, -16 bitop3:0x6c
	v_add3_u32 v175, v35, v173, v27
	ds_write_b16 v175, v29 offset:55552
	v_fma_f32 v29, v172, v18, v215
	v_cvt_pk_bf16_f32 v29, v29, v29
	v_bitop3_b32 v172, v45, 32, -16 bitop3:0x6c
	v_add3_u32 v176, v35, v172, v27
	ds_write_b16 v176, v29 offset:55808
	v_fma_f32 v29, v171, v18, v215
	v_cvt_pk_bf16_f32 v29, v29, v29
	v_bitop3_b32 v171, v45, 48, -16 bitop3:0x6c
	v_add3_u32 v177, v35, v171, v27
	ds_write_b16 v177, v29 offset:56064
	v_fma_f32 v29, v170, v18, v215
	v_cvt_pk_bf16_f32 v29, v29, v29
	v_bitop3_b32 v170, v45, 64, -16 bitop3:0x6c
	v_add3_u32 v178, v35, v170, v27
	ds_write_b16 v178, v29 offset:56320
	v_fma_f32 v29, v169, v18, v215
	v_cvt_pk_bf16_f32 v29, v29, v29
	v_bitop3_b32 v169, v45, s34, -16 bitop3:0x6c
	v_add3_u32 v179, v35, v169, v27
	ds_write_b16 v179, v29 offset:56576
	v_fma_f32 v29, v167, v18, v215
	v_cvt_pk_bf16_f32 v29, v29, v29
	v_bitop3_b32 v167, v45, s31, -16 bitop3:0x6c
	v_add3_u32 v182, v35, v167, v27
	ds_write_b16 v182, v29 offset:56832
	v_fma_f32 v29, v165, v18, v215
	v_cvt_pk_bf16_f32 v29, v29, v29
	v_bitop3_b32 v165, v45, s13, -16 bitop3:0x6c
	v_add3_u32 v183, v35, v165, v27
	ds_write_b16 v183, v29 offset:57088
	v_fma_f32 v29, v168, v18, v215
	v_cvt_pk_bf16_f32 v29, v29, v29
	v_bitop3_b32 v168, v45, s12, -16 bitop3:0x6c
	v_add3_u32 v184, v35, v168, v27
	ds_write_b16 v184, v29 offset:57344
	v_fma_f32 v29, v166, v18, v215
	v_cvt_pk_bf16_f32 v29, v29, v29
	v_bitop3_b32 v166, v45, s35, -16 bitop3:0x6c
	v_add3_u32 v185, v35, v166, v27
	ds_write_b16 v185, v29 offset:57600
	v_fma_f32 v29, v164, v18, v215
	v_cvt_pk_bf16_f32 v29, v29, v29
	v_bitop3_b32 v164, v45, s38, -16 bitop3:0x6c
	v_add3_u32 v186, v35, v164, v27
	ds_write_b16 v186, v29 offset:57856
	v_fma_f32 v29, v153, v18, v215
	v_cvt_pk_bf16_f32 v29, v29, v29
	v_bitop3_b32 v153, v45, s39, -16 bitop3:0x6c
	v_add3_u32 v187, v35, v153, v27
	ds_write_b16 v187, v29 offset:58112
	v_fma_f32 v29, v152, v18, v215
	v_cvt_pk_bf16_f32 v29, v29, v29
	v_bitop3_b32 v152, v45, s16, -16 bitop3:0x6c
	v_add3_u32 v188, v35, v152, v27
	ds_write_b16 v188, v29 offset:58368
	v_fma_f32 v29, v151, v18, v215
	v_cvt_pk_bf16_f32 v29, v29, v29
	v_bitop3_b32 v151, v45, s40, -16 bitop3:0x6c
	v_add3_u32 v189, v35, v151, v27
	ds_write_b16 v189, v29 offset:58624
	v_fma_f32 v29, v148, v18, v215
	v_cvt_pk_bf16_f32 v29, v29, v29
	v_bitop3_b32 v148, v45, s41, -16 bitop3:0x6c
	v_add3_u32 v190, v35, v148, v27
	ds_write_b16 v190, v29 offset:58880
	v_sub_f32_e32 v29, v146, v39
	v_mul_f32_e32 v29, v29, v18
	v_bfe_u32 v146, v29, 16, 1
	v_bitop3_b32 v45, v45, s42, -16 bitop3:0x6c
	v_add_u32_e32 v38, 0xd800, v35
	v_add3_u32 v29, v29, v146, s15
	v_add3_u32 v35, v35, v45, v27
	ds_write_b16_d16_hi v35, v29 offset:59136
	v_fma_f32 v29, v150, v18, v215
	v_cvt_pk_bf16_f32 v29, v29, v29
	ds_write_b16 v174, v29 offset:59392
	v_fma_f32 v29, v149, v18, v215
	v_cvt_pk_bf16_f32 v29, v29, v29
	ds_write_b16 v175, v29 offset:59648
	v_fma_f32 v29, v147, v18, v215
	v_cvt_pk_bf16_f32 v29, v29, v29
	ds_write_b16 v176, v29 offset:59904
	v_fma_f32 v29, v145, v18, v215
	v_cvt_pk_bf16_f32 v29, v29, v29
	ds_write_b16 v177, v29 offset:60160
	v_fma_f32 v29, v143, v18, v215
	v_cvt_pk_bf16_f32 v29, v29, v29
	ds_write_b16 v178, v29 offset:60416
	v_fma_f32 v29, v141, v18, v215
	v_cvt_pk_bf16_f32 v29, v29, v29
	ds_write_b16 v179, v29 offset:60672
	v_fma_f32 v29, v139, v18, v215
	v_cvt_pk_bf16_f32 v29, v29, v29
	ds_write_b16 v182, v29 offset:60928
	v_fma_f32 v29, v137, v18, v215
	v_cvt_pk_bf16_f32 v29, v29, v29
	ds_write_b16 v183, v29 offset:61184
	v_fma_f32 v29, v144, v18, v215
	v_cvt_pk_bf16_f32 v29, v29, v29
	ds_write_b16 v184, v29 offset:61440
	v_fma_f32 v29, v142, v18, v215
	v_cvt_pk_bf16_f32 v29, v29, v29
	ds_write_b16 v185, v29 offset:61696
	v_fma_f32 v29, v140, v18, v215
	v_cvt_pk_bf16_f32 v29, v29, v29
	ds_write_b16 v186, v29 offset:61952
	v_fma_f32 v29, v138, v18, v215
	v_cvt_pk_bf16_f32 v29, v29, v29
	ds_write_b16 v187, v29 offset:62208
	v_fma_f32 v29, v133, v18, v215
	v_cvt_pk_bf16_f32 v29, v29, v29
	ds_write_b16 v188, v29 offset:62464
	v_fma_f32 v29, v131, v18, v215
	v_cvt_pk_bf16_f32 v29, v29, v29
	ds_write_b16 v189, v29 offset:62720
	v_fma_f32 v29, v64, v18, v215
	v_cvt_pk_bf16_f32 v29, v29, v29
	ds_write_b16 v190, v29 offset:62976
	v_fma_f32 v29, v62, v18, v215
	v_cvt_pk_bf16_f32 v29, v29, v29
	ds_write_b16 v35, v29 offset:63232
	v_fma_f32 v29, v136, v18, v215
	v_cvt_pk_bf16_f32 v29, v29, v29
	ds_write_b16 v174, v29 offset:63488
	v_fma_f32 v29, v132, v18, v215
	v_cvt_pk_bf16_f32 v29, v29, v29
	ds_write_b16 v175, v29 offset:63744
	v_fma_f32 v29, v65, v18, v215
	v_cvt_pk_bf16_f32 v29, v29, v29
	ds_write_b16 v176, v29 offset:64000
	v_fma_f32 v29, v63, v18, v215
	v_cvt_pk_bf16_f32 v29, v29, v29
	ds_write_b16 v177, v29 offset:64256
	v_fma_f32 v29, v60, v18, v215
	v_cvt_pk_bf16_f32 v29, v29, v29
	ds_write_b16 v178, v29 offset:64512
	v_fma_f32 v29, v59, v18, v215
	v_cvt_pk_bf16_f32 v29, v29, v29
	ds_write_b16 v179, v29 offset:64768
	v_fma_f32 v29, v57, v18, v215
	v_cvt_pk_bf16_f32 v29, v29, v29
	ds_write_b16 v182, v29 offset:65024
	v_fma_f32 v29, v55, v18, v215
	v_cvt_pk_bf16_f32 v29, v29, v29
	ds_write_b16 v183, v29 offset:65280
	v_fma_f32 v29, v61, v18, v215
	v_cvt_pk_bf16_f32 v29, v29, v29
	v_add3_u32 v35, v38, v168, v27
	ds_write_b16 v35, v29 offset:10240
	v_fma_f32 v29, v58, v18, v215
	v_cvt_pk_bf16_f32 v29, v29, v29
	v_add3_u32 v55, v38, v166, v27
	ds_write_b16 v55, v29 offset:10496
	v_fma_f32 v29, v56, v18, v215
	v_cvt_pk_bf16_f32 v29, v29, v29
	v_add3_u32 v56, v38, v164, v27
	ds_write_b16 v56, v29 offset:10752
	v_fma_f32 v29, v54, v18, v215
	v_cvt_pk_bf16_f32 v29, v29, v29
	v_add3_u32 v54, v38, v153, v27
	ds_write_b16 v54, v29 offset:11008
	v_fma_f32 v29, v53, v18, v215
	v_cvt_pk_bf16_f32 v29, v29, v29
	v_add3_u32 v53, v38, v152, v27
	ds_write_b16 v53, v29 offset:11264
	v_fma_f32 v29, v51, v18, v215
	v_cvt_pk_bf16_f32 v29, v29, v29
	v_add3_u32 v51, v38, v151, v27
	ds_write_b16 v51, v29 offset:11520
	v_fma_f32 v29, v49, v18, v215
	v_cvt_pk_bf16_f32 v29, v29, v29
	v_add3_u32 v49, v38, v148, v27
	ds_write_b16 v49, v29 offset:11776
	v_fma_f32 v29, v47, v18, v215
	v_cvt_pk_bf16_f32 v29, v29, v29
	v_add3_u32 v45, v38, v45, v27
	ds_write_b16 v45, v29 offset:12032
	v_fma_f32 v29, v52, v18, v215
	v_cvt_pk_bf16_f32 v29, v29, v29
	v_add3_u32 v46, v38, v46, v27
	ds_write_b16 v46, v29 offset:12288
	v_fma_f32 v29, v50, v18, v215
	v_cvt_pk_bf16_f32 v29, v29, v29
	v_add3_u32 v46, v38, v173, v27
	ds_write_b16 v46, v29 offset:12544
	v_fma_f32 v29, v48, v18, v215
	v_cvt_pk_bf16_f32 v29, v29, v29
	v_add3_u32 v46, v38, v172, v27
	ds_write_b16 v46, v29 offset:12800
	v_mul_f32_e32 v29, v37, v18
	v_bfe_u32 v36, v29, 16, 1
	v_add3_u32 v29, v29, v36, s15
	v_add3_u32 v36, v38, v171, v27
	ds_write_b16_d16_hi v36, v29 offset:13056
	v_fma_f32 v29, v34, v18, v215
	v_cvt_pk_bf16_f32 v29, v29, v29
	v_add3_u32 v34, v38, v170, v27
	ds_write_b16 v34, v29 offset:13312
	v_sub_f32_e32 v29, v24, v39
	v_pk_fma_f32 v[24:25], v[40:41], s[22:23], v[24:25] op_sel_hi:[1,0,1] neg_lo:[1,0,0] neg_hi:[1,0,0]
	v_mul_f32_e32 v29, v29, v18
	v_mul_f32_e32 v24, v25, v18
	v_bfe_u32 v34, v29, 16, 1
	v_bfe_u32 v25, v24, 16, 1
	v_add3_u32 v29, v29, v34, s15
	v_add3_u32 v34, v38, v169, v27
	v_add3_u32 v24, v24, v25, s15
	v_add3_u32 v25, v38, v167, v27
	ds_write_b16_d16_hi v34, v29 offset:13568
	ds_write_b16_d16_hi v25, v24 offset:13824
	v_pk_fma_f32 v[24:25], v[40:41], s[22:23], v[32:33] op_sel_hi:[1,0,1] neg_lo:[1,0,0] neg_hi:[1,0,0]
	v_and_b32_e32 v133, 15, v43
	v_mul_f32_e32 v24, v25, v18
	v_bfe_u32 v25, v24, 16, 1
	v_add3_u32 v24, v24, v25, s15
	v_add3_u32 v25, v38, v165, v27
	ds_write_b16_d16_hi v25, v24 offset:14080
	v_fma_f32 v24, v28, v18, v215
	v_cvt_pk_bf16_f32 v24, v24, v24
	ds_write_b16 v35, v24 offset:14336
	v_sub_f32_e32 v24, v22, v39
	v_pk_fma_f32 v[22:23], v[40:41], s[22:23], v[22:23] op_sel_hi:[1,0,1] neg_lo:[1,0,0] neg_hi:[1,0,0]
	v_mul_f32_e32 v24, v24, v18
	v_mul_f32_e32 v22, v23, v18
	v_bfe_u32 v25, v24, 16, 1
	v_bfe_u32 v23, v22, 16, 1
	v_add3_u32 v24, v24, v25, s15
	v_add3_u32 v22, v22, v23, s15
	ds_write_b16_d16_hi v55, v24 offset:14592
	ds_write_b16_d16_hi v56, v22 offset:14848
	v_pk_fma_f32 v[22:23], v[40:41], s[22:23], v[30:31] op_sel_hi:[1,0,1] neg_lo:[1,0,0] neg_hi:[1,0,0]
	s_nop 0
	v_mul_f32_e32 v22, v23, v18
	v_bfe_u32 v23, v22, 16, 1
	v_add3_u32 v22, v22, v23, s15
	ds_write_b16_d16_hi v54, v22 offset:15104
	v_fma_f32 v22, v26, v18, v215
	v_cvt_pk_bf16_f32 v22, v22, v22
	ds_write_b16 v53, v22 offset:15360
	v_sub_f32_e32 v22, v20, v39
	v_pk_fma_f32 v[20:21], v[40:41], s[22:23], v[20:21] op_sel_hi:[1,0,1] neg_lo:[1,0,0] neg_hi:[1,0,0]
	v_mul_f32_e32 v22, v22, v18
	v_mul_f32_e32 v20, v21, v18
	v_mul_f32_e32 v18, v19, v18
	v_bfe_u32 v23, v22, 16, 1
	v_bfe_u32 v21, v20, 16, 1
	v_bfe_u32 v19, v18, 16, 1
	v_add3_u32 v22, v22, v23, s15
	v_add3_u32 v20, v20, v21, s15
	v_add3_u32 v18, v18, v19, s15
	ds_write_b16_d16_hi v51, v22 offset:15616
	ds_write_b16_d16_hi v49, v20 offset:15872
	ds_write_b16_d16_hi v45, v18 offset:16128
	v_lshrrev_b32_e32 v18, 1, v43
	v_and_b32_e32 v18, 32, v18
	v_lshl_or_b32 v132, v44, 6, v18
	v_or_b32_e32 v18, v132, v134
	v_lshl_add_u32 v131, v18, 8, 32
	v_bitop3_b32 v18, v42, v133, 1 bitop3:0x6c
	v_lshl_add_u32 v18, v18, 4, v131
	s_waitcnt lgkmcnt(0)
	s_barrier
	ds_read_b128 v[136:139], v18 offset:55296
	s_waitcnt lgkmcnt(0)
	v_mfma_f32_32x32x16_bf16 v[50:65], v[136:139], v[2:5], 0
	v_mfma_f32_32x32x16_bf16 v[34:49], v[136:139], v[6:9], 0
	v_mfma_f32_32x32x16_bf16 v[18:33], v[136:139], v[10:13], 0
	v_mfma_f32_32x32x16_bf16 v[2:17], v[136:139], v[14:17], 0
	v_bitop3_b32 v136, v135, v133, 2 bitop3:0x36
	v_lshl_add_u32 v136, v136, 4, v131
	ds_read_b128 v[136:139], v136 offset:55296
	s_waitcnt lgkmcnt(0)
	v_mfma_f32_32x32x16_bf16 v[50:65], v[136:139], v[114:117], v[50:65]
	v_bitop3_b32 v114, v135, v133, 4 bitop3:0x36
	v_lshl_add_u32 v114, v114, 4, v131
	ds_read_b128 v[114:117], v114 offset:55296
	v_mfma_f32_32x32x16_bf16 v[34:49], v[136:139], v[118:121], v[34:49]
	v_mfma_f32_32x32x16_bf16 v[18:33], v[136:139], v[122:125], v[18:33]
	s_waitcnt lgkmcnt(0)
	v_mfma_f32_32x32x16_bf16 v[34:49], v[114:117], v[102:105], v[34:49]
	v_bitop3_b32 v102, v135, v133, 6 bitop3:0x36
	v_lshl_add_u32 v102, v102, 4, v131
	ds_read_b128 v[102:105], v102 offset:55296
	v_mfma_f32_32x32x16_bf16 v[2:17], v[136:139], v[126:129], v[2:17]
	v_mfma_f32_32x32x16_bf16 v[18:33], v[114:117], v[106:109], v[18:33]
	s_waitcnt lgkmcnt(0)
	v_mfma_f32_32x32x16_bf16 v[34:49], v[102:105], v[90:93], v[34:49]
	v_bitop3_b32 v90, v135, v133, 8 bitop3:0x36
	v_lshl_add_u32 v90, v90, 4, v131
	ds_read_b128 v[90:93], v90 offset:55296
	v_mfma_f32_32x32x16_bf16 v[2:17], v[114:117], v[110:113], v[2:17]
	v_mfma_f32_32x32x16_bf16 v[18:33], v[102:105], v[94:97], v[18:33]
	v_mfma_f32_32x32x16_bf16 v[2:17], v[102:105], v[98:101], v[2:17]
	v_lshlrev_b32_e32 v104, 7, v130
	v_or_b32_e32 v102, v104, v134
	v_ashrrev_i32_e32 v103, 31, v102
	v_lshlrev_b64 v[106:107], 2, v[102:103]
	v_lshl_or_b32 v98, v135, 2, v132
	v_or_b32_e32 v100, s3, v134
	v_mov_b32_e32 v101, s5
	s_waitcnt lgkmcnt(0)
	v_mfma_f32_32x32x16_bf16 v[18:33], v[90:93], v[82:85], v[18:33]
	v_bitop3_b32 v82, v135, v133, 10 bitop3:0x36
	v_lshl_add_u32 v82, v82, 4, v131
	ds_read_b128 v[82:85], v82 offset:55296
	v_lshl_add_u64 v[108:109], s[6:7], 0, v[106:107]
	v_lshl_add_u64 v[106:107], s[92:93], 0, v[106:107]
	v_ashrrev_i32_e32 v99, 31, v98
	v_lshlrev_b64 v[98:99], 1, v[98:99]
	v_mfma_f32_32x32x16_bf16 v[2:17], v[90:93], v[86:89], v[2:17]
	s_add_i32 s3, s3, s18
	s_cmpk_gt_i32 s4, 0x7f
	s_waitcnt lgkmcnt(0)
	v_mfma_f32_32x32x16_bf16 v[18:33], v[82:85], v[74:77], v[18:33]
	v_bitop3_b32 v74, v135, v133, 12 bitop3:0x36
	v_lshl_add_u32 v74, v74, 4, v131
	ds_read_b128 v[74:77], v74 offset:55296
	v_mfma_f32_32x32x16_bf16 v[2:17], v[82:85], v[78:81], v[2:17]
	s_waitcnt lgkmcnt(0)
	v_mfma_f32_32x32x16_bf16 v[2:17], v[74:77], v[70:73], v[2:17]
	v_bitop3_b32 v70, v135, v133, 14 bitop3:0x36
	v_lshl_add_u32 v70, v70, 4, v131
	ds_read_b128 v[70:73], v70 offset:55296
	v_ashrrev_i32_e32 v133, 31, v132
	s_waitcnt lgkmcnt(0)
	v_mfma_f32_32x32x16_bf16 v[2:17], v[70:73], v[66:69], v[2:17]
	v_lshlrev_b64 v[66:67], 2, v[132:133]
	v_lshl_add_u64 v[68:69], s[10:11], 0, v[66:67]
	v_lshl_add_u64 v[66:67], s[36:37], 0, v[66:67]
	v_lshl_add_u64 v[68:69], v[68:69], 0, v[154:155]
	v_lshl_add_u64 v[70:71], v[66:67], 0, v[154:155]
	global_load_dwordx4 v[90:93], v[68:69], off
	global_load_dwordx4 v[94:97], v[70:71], off
	global_load_dwordx4 v[82:85], v[68:69], off offset:32
	global_load_dwordx4 v[86:89], v[70:71], off offset:32
	global_load_dwordx4 v[74:77], v[68:69], off offset:64
	global_load_dwordx4 v[78:81], v[70:71], off offset:64
	s_nop 0
	global_load_dwordx4 v[66:69], v[68:69], off offset:96
	s_nop 0
	global_load_dwordx4 v[70:73], v[70:71], off offset:96
	s_nop 0
	global_load_dword v118, v[108:109], off
	global_load_dword v119, v[108:109], off offset:128
	global_load_dword v120, v[108:109], off offset:256
	global_load_dword v121, v[108:109], off offset:384
	global_load_dword v122, v[106:107], off
	global_load_dword v123, v[106:107], off offset:128
	global_load_dword v124, v[106:107], off offset:256
	global_load_dword v125, v[106:107], off offset:384
	v_lshlrev_b64 v[110:111], 11, v[100:101]
	v_lshl_add_u64 v[110:111], s[62:63], 0, v[110:111]
	v_lshl_add_u64 v[110:111], v[110:111], 0, v[98:99]
	v_add_co_u32_e32 v112, vcc, 0x10000, v110
	s_nop 1
	v_addc_co_u32_e32 v113, vcc, 0, v111, vcc
	v_add_co_u32_e32 v114, vcc, 0x20000, v110
	s_nop 1
	v_addc_co_u32_e32 v115, vcc, 0, v111, vcc
	v_add_co_u32_e32 v116, vcc, 0x30000, v110
	s_nop 1
	v_addc_co_u32_e32 v117, vcc, 0, v111, vcc
	s_barrier
	v_and_b32_e32 v126, 31, v0
	v_lshlrev_b32_e32 v136, 6, v126
	v_bfe_u32 v127, v0, 5, 1
	v_lshl_add_u32 v136, v127, 3, v136
	v_lshrrev_b32_e32 v134, 6, v0
	v_lshl_add_u32 v136, v134, 13, v136
	v_add_u32_e32 v136, 0xd820, v136
	v_bfe_u32 v126, v0, 1, 2
	v_xor_b32_e32 v127, 0, v126
	v_lshl_add_u32 v128, v127, 4, v136
	v_xor_b32_e32 v127, 1, v126
	v_lshl_add_u32 v129, v127, 4, v136
	v_xor_b32_e32 v127, 2, v126
	v_lshl_add_u32 v130, v127, 4, v136
	v_xor_b32_e32 v127, 3, v126
	v_lshl_add_u32 v131, v127, 4, v136
	v_bfe_u32 v135, v0, 2, 4
	v_lshlrev_b32_e32 v132, 6, v135
	v_and_b32_e32 v127, 3, v0
	v_bfe_u32 v126, v0, 3, 2
	v_xor_b32_e32 v126, v127, v126
	v_lshl_add_u32 v132, v126, 4, v132
	v_lshl_add_u32 v132, v134, 13, v132
	v_add_u32_e32 v132, 0xd820, v132
	v_and_b32_e32 v133, -32, v100
	v_add_u32_e32 v133, v133, v135
	v_lshlrev_b32_e32 v133, 11, v133
	v_lshl_add_u32 v133, v134, 6, v133
	v_lshl_add_u32 v133, v127, 4, v133
	s_waitcnt vmcnt(0)
	s_nop 1
	v_permlane32_swap_b32 v216, v218
	v_permlane32_swap_b32 v217, v219
	v_permlane32_swap_b32 v220, v222
	v_permlane32_swap_b32 v221, v223
	v_permlane32_swap_b32 v224, v226
	v_permlane32_swap_b32 v225, v227
	v_permlane32_swap_b32 v228, v230
	v_permlane32_swap_b32 v229, v231
	v_permlane32_swap_b32 v232, v234
	v_permlane32_swap_b32 v233, v235
	v_permlane32_swap_b32 v236, v238
	v_permlane32_swap_b32 v237, v239
	v_permlane32_swap_b32 v252, v254
	v_permlane32_swap_b32 v253, v255
	v_mul_f32_e32 v126, v94, v118
	v_fmac_f32_e32 v126, v50, v90
	v_add_f32_e32 v50, v122, v126
	v_lshlrev_b32_e32 v127, 16, v216
	v_mul_f32_e32 v50, v50, v127
	v_mul_f32_e32 v126, v95, v118
	v_fmac_f32_e32 v126, v51, v91
	v_add_f32_e32 v51, v122, v126
	v_and_b32_e32 v127, 0xffff0000, v216
	v_mul_f32_e32 v51, v51, v127
	v_mul_f32_e32 v126, v96, v118
	v_fmac_f32_e32 v126, v52, v92
	v_add_f32_e32 v52, v122, v126
	v_lshlrev_b32_e32 v127, 16, v217
	v_mul_f32_e32 v52, v52, v127
	v_mul_f32_e32 v126, v97, v118
	v_fmac_f32_e32 v126, v53, v93
	v_add_f32_e32 v53, v122, v126
	v_and_b32_e32 v127, 0xffff0000, v217
	v_mul_f32_e32 v53, v53, v127
	v_cvt_pk_bf16_f32 v50, v50, v51
	v_cvt_pk_bf16_f32 v51, v52, v53
	ds_write_b64 v128, v[50:51] offset:0
	v_mul_f32_e32 v126, v86, v118
	v_fmac_f32_e32 v126, v54, v82
	v_add_f32_e32 v54, v122, v126
	v_lshlrev_b32_e32 v127, 16, v218
	v_mul_f32_e32 v54, v54, v127
	v_mul_f32_e32 v126, v87, v118
	v_fmac_f32_e32 v126, v55, v83
	v_add_f32_e32 v55, v122, v126
	v_and_b32_e32 v127, 0xffff0000, v218
	v_mul_f32_e32 v55, v55, v127
	v_mul_f32_e32 v126, v88, v118
	v_fmac_f32_e32 v126, v56, v84
	v_add_f32_e32 v56, v122, v126
	v_lshlrev_b32_e32 v127, 16, v219
	v_mul_f32_e32 v56, v56, v127
	v_mul_f32_e32 v126, v89, v118
	v_fmac_f32_e32 v126, v57, v85
	v_add_f32_e32 v57, v122, v126
	v_and_b32_e32 v127, 0xffff0000, v219
	v_mul_f32_e32 v57, v57, v127
	v_cvt_pk_bf16_f32 v54, v54, v55
	v_cvt_pk_bf16_f32 v55, v56, v57
	ds_write_b64 v129, v[54:55] offset:0
	v_mul_f32_e32 v126, v78, v118
	v_fmac_f32_e32 v126, v58, v74
	v_add_f32_e32 v58, v122, v126
	v_lshlrev_b32_e32 v127, 16, v220
	v_mul_f32_e32 v58, v58, v127
	v_mul_f32_e32 v126, v79, v118
	v_fmac_f32_e32 v126, v59, v75
	v_add_f32_e32 v59, v122, v126
	v_and_b32_e32 v127, 0xffff0000, v220
	v_mul_f32_e32 v59, v59, v127
	v_mul_f32_e32 v126, v80, v118
	v_fmac_f32_e32 v126, v60, v76
	v_add_f32_e32 v60, v122, v126
	v_lshlrev_b32_e32 v127, 16, v221
	v_mul_f32_e32 v60, v60, v127
	v_mul_f32_e32 v126, v81, v118
	v_fmac_f32_e32 v126, v61, v77
	v_add_f32_e32 v61, v122, v126
	v_and_b32_e32 v127, 0xffff0000, v221
	v_mul_f32_e32 v61, v61, v127
	v_cvt_pk_bf16_f32 v58, v58, v59
	v_cvt_pk_bf16_f32 v59, v60, v61
	ds_write_b64 v130, v[58:59] offset:0
	v_mul_f32_e32 v126, v70, v118
	v_fmac_f32_e32 v126, v62, v66
	v_add_f32_e32 v62, v122, v126
	v_lshlrev_b32_e32 v127, 16, v222
	v_mul_f32_e32 v62, v62, v127
	v_mul_f32_e32 v126, v71, v118
	v_fmac_f32_e32 v126, v63, v67
	v_add_f32_e32 v63, v122, v126
	v_and_b32_e32 v127, 0xffff0000, v222
	v_mul_f32_e32 v63, v63, v127
	v_mul_f32_e32 v126, v72, v118
	v_fmac_f32_e32 v126, v64, v68
	v_add_f32_e32 v64, v122, v126
	v_lshlrev_b32_e32 v127, 16, v223
	v_mul_f32_e32 v64, v64, v127
	v_mul_f32_e32 v126, v73, v118
	v_fmac_f32_e32 v126, v65, v69
	v_add_f32_e32 v65, v122, v126
	v_and_b32_e32 v127, 0xffff0000, v223
	v_mul_f32_e32 v65, v65, v127
	v_cvt_pk_bf16_f32 v62, v62, v63
	v_cvt_pk_bf16_f32 v63, v64, v65
	ds_write_b64 v131, v[62:63] offset:0
	v_mul_f32_e32 v126, v94, v119
	v_fmac_f32_e32 v126, v34, v90
	v_add_f32_e32 v34, v123, v126
	v_lshlrev_b32_e32 v127, 16, v224
	v_mul_f32_e32 v34, v34, v127
	v_mul_f32_e32 v126, v95, v119
	v_fmac_f32_e32 v126, v35, v91
	v_add_f32_e32 v35, v123, v126
	v_and_b32_e32 v127, 0xffff0000, v224
	v_mul_f32_e32 v35, v35, v127
	v_mul_f32_e32 v126, v96, v119
	v_fmac_f32_e32 v126, v36, v92
	v_add_f32_e32 v36, v123, v126
	v_lshlrev_b32_e32 v127, 16, v225
	v_mul_f32_e32 v36, v36, v127
	v_mul_f32_e32 v126, v97, v119
	v_fmac_f32_e32 v126, v37, v93
	v_add_f32_e32 v37, v123, v126
	v_and_b32_e32 v127, 0xffff0000, v225
	v_mul_f32_e32 v37, v37, v127
	v_cvt_pk_bf16_f32 v34, v34, v35
	v_cvt_pk_bf16_f32 v35, v36, v37
	ds_write_b64 v128, v[34:35] offset:2048
	v_mul_f32_e32 v126, v86, v119
	v_fmac_f32_e32 v126, v38, v82
	v_add_f32_e32 v38, v123, v126
	v_lshlrev_b32_e32 v127, 16, v226
	v_mul_f32_e32 v38, v38, v127
	v_mul_f32_e32 v126, v87, v119
	v_fmac_f32_e32 v126, v39, v83
	v_add_f32_e32 v39, v123, v126
	v_and_b32_e32 v127, 0xffff0000, v226
	v_mul_f32_e32 v39, v39, v127
	v_mul_f32_e32 v126, v88, v119
	v_fmac_f32_e32 v126, v40, v84
	v_add_f32_e32 v40, v123, v126
	v_lshlrev_b32_e32 v127, 16, v227
	v_mul_f32_e32 v40, v40, v127
	v_mul_f32_e32 v126, v89, v119
	v_fmac_f32_e32 v126, v41, v85
	v_add_f32_e32 v41, v123, v126
	v_and_b32_e32 v127, 0xffff0000, v227
	v_mul_f32_e32 v41, v41, v127
	v_cvt_pk_bf16_f32 v38, v38, v39
	v_cvt_pk_bf16_f32 v39, v40, v41
	ds_write_b64 v129, v[38:39] offset:2048
	v_mul_f32_e32 v126, v78, v119
	v_fmac_f32_e32 v126, v42, v74
	v_add_f32_e32 v42, v123, v126
	v_lshlrev_b32_e32 v127, 16, v228
	v_mul_f32_e32 v42, v42, v127
	v_mul_f32_e32 v126, v79, v119
	v_fmac_f32_e32 v126, v43, v75
	v_add_f32_e32 v43, v123, v126
	v_and_b32_e32 v127, 0xffff0000, v228
	v_mul_f32_e32 v43, v43, v127
	v_mul_f32_e32 v126, v80, v119
	v_fmac_f32_e32 v126, v44, v76
	v_add_f32_e32 v44, v123, v126
	v_lshlrev_b32_e32 v127, 16, v229
	v_mul_f32_e32 v44, v44, v127
	v_mul_f32_e32 v126, v81, v119
	v_fmac_f32_e32 v126, v45, v77
	v_add_f32_e32 v45, v123, v126
	v_and_b32_e32 v127, 0xffff0000, v229
	v_mul_f32_e32 v45, v45, v127
	v_cvt_pk_bf16_f32 v42, v42, v43
	v_cvt_pk_bf16_f32 v43, v44, v45
	ds_write_b64 v130, v[42:43] offset:2048
	v_mul_f32_e32 v126, v70, v119
	v_fmac_f32_e32 v126, v46, v66
	v_add_f32_e32 v46, v123, v126
	v_lshlrev_b32_e32 v127, 16, v230
	v_mul_f32_e32 v46, v46, v127
	v_mul_f32_e32 v126, v71, v119
	v_fmac_f32_e32 v126, v47, v67
	v_add_f32_e32 v47, v123, v126
	v_and_b32_e32 v127, 0xffff0000, v230
	v_mul_f32_e32 v47, v47, v127
	v_mul_f32_e32 v126, v72, v119
	v_fmac_f32_e32 v126, v48, v68
	v_add_f32_e32 v48, v123, v126
	v_lshlrev_b32_e32 v127, 16, v231
	v_mul_f32_e32 v48, v48, v127
	v_mul_f32_e32 v126, v73, v119
	v_fmac_f32_e32 v126, v49, v69
	v_add_f32_e32 v49, v123, v126
	v_and_b32_e32 v127, 0xffff0000, v231
	v_mul_f32_e32 v49, v49, v127
	v_cvt_pk_bf16_f32 v46, v46, v47
	v_cvt_pk_bf16_f32 v47, v48, v49
	ds_write_b64 v131, v[46:47] offset:2048
	v_mul_f32_e32 v126, v94, v120
	v_fmac_f32_e32 v126, v18, v90
	v_add_f32_e32 v18, v124, v126
	v_lshlrev_b32_e32 v127, 16, v232
	v_mul_f32_e32 v18, v18, v127
	v_mul_f32_e32 v126, v95, v120
	v_fmac_f32_e32 v126, v19, v91
	v_add_f32_e32 v19, v124, v126
	v_and_b32_e32 v127, 0xffff0000, v232
	v_mul_f32_e32 v19, v19, v127
	v_mul_f32_e32 v126, v96, v120
	v_fmac_f32_e32 v126, v20, v92
	v_add_f32_e32 v20, v124, v126
	v_lshlrev_b32_e32 v127, 16, v233
	v_mul_f32_e32 v20, v20, v127
	v_mul_f32_e32 v126, v97, v120
	v_fmac_f32_e32 v126, v21, v93
	v_add_f32_e32 v21, v124, v126
	v_and_b32_e32 v127, 0xffff0000, v233
	v_mul_f32_e32 v21, v21, v127
	v_cvt_pk_bf16_f32 v18, v18, v19
	v_cvt_pk_bf16_f32 v19, v20, v21
	ds_write_b64 v128, v[18:19] offset:4096
	v_mul_f32_e32 v126, v86, v120
	v_fmac_f32_e32 v126, v22, v82
	v_add_f32_e32 v22, v124, v126
	v_lshlrev_b32_e32 v127, 16, v234
	v_mul_f32_e32 v22, v22, v127
	v_mul_f32_e32 v126, v87, v120
	v_fmac_f32_e32 v126, v23, v83
	v_add_f32_e32 v23, v124, v126
	v_and_b32_e32 v127, 0xffff0000, v234
	v_mul_f32_e32 v23, v23, v127
	v_mul_f32_e32 v126, v88, v120
	v_fmac_f32_e32 v126, v24, v84
	v_add_f32_e32 v24, v124, v126
	v_lshlrev_b32_e32 v127, 16, v235
	v_mul_f32_e32 v24, v24, v127
	v_mul_f32_e32 v126, v89, v120
	v_fmac_f32_e32 v126, v25, v85
	v_add_f32_e32 v25, v124, v126
	v_and_b32_e32 v127, 0xffff0000, v235
	v_mul_f32_e32 v25, v25, v127
	v_cvt_pk_bf16_f32 v22, v22, v23
	v_cvt_pk_bf16_f32 v23, v24, v25
	ds_write_b64 v129, v[22:23] offset:4096
	v_mul_f32_e32 v126, v78, v120
	v_fmac_f32_e32 v126, v26, v74
	v_add_f32_e32 v26, v124, v126
	v_lshlrev_b32_e32 v127, 16, v236
	v_mul_f32_e32 v26, v26, v127
	v_mul_f32_e32 v126, v79, v120
	v_fmac_f32_e32 v126, v27, v75
	v_add_f32_e32 v27, v124, v126
	v_and_b32_e32 v127, 0xffff0000, v236
	v_mul_f32_e32 v27, v27, v127
	v_mul_f32_e32 v126, v80, v120
	v_fmac_f32_e32 v126, v28, v76
	v_add_f32_e32 v28, v124, v126
	v_lshlrev_b32_e32 v127, 16, v237
	v_mul_f32_e32 v28, v28, v127
	v_mul_f32_e32 v126, v81, v120
	v_fmac_f32_e32 v126, v29, v77
	v_add_f32_e32 v29, v124, v126
	v_and_b32_e32 v127, 0xffff0000, v237
	v_mul_f32_e32 v29, v29, v127
	v_cvt_pk_bf16_f32 v26, v26, v27
	v_cvt_pk_bf16_f32 v27, v28, v29
	ds_write_b64 v130, v[26:27] offset:4096
	v_mul_f32_e32 v126, v70, v120
	v_fmac_f32_e32 v126, v30, v66
	v_add_f32_e32 v30, v124, v126
	v_lshlrev_b32_e32 v127, 16, v238
	v_mul_f32_e32 v30, v30, v127
	v_mul_f32_e32 v126, v71, v120
	v_fmac_f32_e32 v126, v31, v67
	v_add_f32_e32 v31, v124, v126
	v_and_b32_e32 v127, 0xffff0000, v238
	v_mul_f32_e32 v31, v31, v127
	v_mul_f32_e32 v126, v72, v120
	v_fmac_f32_e32 v126, v32, v68
	v_add_f32_e32 v32, v124, v126
	v_lshlrev_b32_e32 v127, 16, v239
	v_mul_f32_e32 v32, v32, v127
	v_mul_f32_e32 v126, v73, v120
	v_fmac_f32_e32 v126, v33, v69
	v_add_f32_e32 v33, v124, v126
	v_and_b32_e32 v127, 0xffff0000, v239
	v_mul_f32_e32 v33, v33, v127
	v_cvt_pk_bf16_f32 v30, v30, v31
	v_cvt_pk_bf16_f32 v31, v32, v33
	ds_write_b64 v131, v[30:31] offset:4096
	v_mul_f32_e32 v126, v94, v121
	v_fmac_f32_e32 v126, v2, v90
	v_add_f32_e32 v2, v125, v126
	v_lshlrev_b32_e32 v127, 16, v252
	v_mul_f32_e32 v2, v2, v127
	v_mul_f32_e32 v126, v95, v121
	v_fmac_f32_e32 v126, v3, v91
	v_add_f32_e32 v3, v125, v126
	v_and_b32_e32 v127, 0xffff0000, v252
	v_mul_f32_e32 v3, v3, v127
	v_mul_f32_e32 v126, v96, v121
	v_fmac_f32_e32 v126, v4, v92
	v_add_f32_e32 v4, v125, v126
	v_lshlrev_b32_e32 v127, 16, v253
	v_mul_f32_e32 v4, v4, v127
	v_mul_f32_e32 v126, v97, v121
	v_fmac_f32_e32 v126, v5, v93
	v_add_f32_e32 v5, v125, v126
	v_and_b32_e32 v127, 0xffff0000, v253
	v_mul_f32_e32 v5, v5, v127
	v_cvt_pk_bf16_f32 v2, v2, v3
	v_cvt_pk_bf16_f32 v3, v4, v5
	ds_write_b64 v128, v[2:3] offset:6144
	v_mul_f32_e32 v126, v86, v121
	v_fmac_f32_e32 v126, v6, v82
	v_add_f32_e32 v6, v125, v126
	v_lshlrev_b32_e32 v127, 16, v254
	v_mul_f32_e32 v6, v6, v127
	v_mul_f32_e32 v126, v87, v121
	v_fmac_f32_e32 v126, v7, v83
	v_add_f32_e32 v7, v125, v126
	v_and_b32_e32 v127, 0xffff0000, v254
	v_mul_f32_e32 v7, v7, v127
	v_mul_f32_e32 v126, v88, v121
	v_fmac_f32_e32 v126, v8, v84
	v_add_f32_e32 v8, v125, v126
	v_lshlrev_b32_e32 v127, 16, v255
	v_mul_f32_e32 v8, v8, v127
	v_mul_f32_e32 v126, v89, v121
	v_fmac_f32_e32 v126, v9, v85
	v_add_f32_e32 v9, v125, v126
	v_and_b32_e32 v127, 0xffff0000, v255
	v_mul_f32_e32 v9, v9, v127
	v_cvt_pk_bf16_f32 v6, v6, v7
	v_cvt_pk_bf16_f32 v7, v8, v9
	ds_write_b64 v129, v[6:7] offset:6144
	v_mul_f32_e32 v126, v78, v121
	v_fmac_f32_e32 v126, v10, v74
	v_add_f32_e32 v10, v125, v126
	v_lshlrev_b32_e32 v127, 16, v240
	v_mul_f32_e32 v10, v10, v127
	v_mul_f32_e32 v126, v79, v121
	v_fmac_f32_e32 v126, v11, v75
	v_add_f32_e32 v11, v125, v126
	v_and_b32_e32 v127, 0xffff0000, v240
	v_mul_f32_e32 v11, v11, v127
	v_mul_f32_e32 v126, v80, v121
	v_fmac_f32_e32 v126, v12, v76
	v_add_f32_e32 v12, v125, v126
	v_lshlrev_b32_e32 v127, 16, v241
	v_mul_f32_e32 v12, v12, v127
	v_mul_f32_e32 v126, v81, v121
	v_fmac_f32_e32 v126, v13, v77
	v_add_f32_e32 v13, v125, v126
	v_and_b32_e32 v127, 0xffff0000, v241
	v_mul_f32_e32 v13, v13, v127
	v_cvt_pk_bf16_f32 v10, v10, v11
	v_cvt_pk_bf16_f32 v11, v12, v13
	ds_write_b64 v130, v[10:11] offset:6144
	v_mul_f32_e32 v126, v70, v121
	v_fmac_f32_e32 v126, v14, v66
	v_add_f32_e32 v14, v125, v126
	v_lshlrev_b32_e32 v127, 16, v246
	v_mul_f32_e32 v14, v14, v127
	v_mul_f32_e32 v126, v71, v121
	v_fmac_f32_e32 v126, v15, v67
	v_add_f32_e32 v15, v125, v126
	v_and_b32_e32 v127, 0xffff0000, v246
	v_mul_f32_e32 v15, v15, v127
	v_mul_f32_e32 v126, v72, v121
	v_fmac_f32_e32 v126, v16, v68
	v_add_f32_e32 v16, v125, v126
	v_lshlrev_b32_e32 v127, 16, v247
	v_mul_f32_e32 v16, v16, v127
	v_mul_f32_e32 v126, v73, v121
	v_fmac_f32_e32 v126, v17, v69
	v_add_f32_e32 v17, v125, v126
	v_and_b32_e32 v127, 0xffff0000, v247
	v_mul_f32_e32 v17, v17, v127
	v_cvt_pk_bf16_f32 v14, v14, v15
	v_cvt_pk_bf16_f32 v15, v16, v17
	ds_write_b64 v131, v[14:15] offset:6144
	s_waitcnt lgkmcnt(0)
	ds_read_b128 v[2:5], v132 offset:0
	ds_read_b128 v[6:9], v132 offset:1024
	ds_read_b128 v[10:13], v132 offset:2048
	ds_read_b128 v[14:17], v132 offset:3072
	ds_read_b128 v[18:21], v132 offset:4096
	ds_read_b128 v[22:25], v132 offset:5120
	ds_read_b128 v[26:29], v132 offset:6144
	ds_read_b128 v[30:33], v132 offset:7168
	s_waitcnt lgkmcnt(7)
	global_store_dwordx4 v133, v[2:5], s[62:63] offset:1536
	v_add_u32_e32 v127, 0x8000, v133
	s_waitcnt lgkmcnt(6)
	global_store_dwordx4 v127, v[6:9], s[62:63] offset:1536
	v_add_u32_e32 v126, 0x10000, v133
	s_waitcnt lgkmcnt(5)
	global_store_dwordx4 v126, v[10:13], s[62:63] offset:1536
	v_add_u32_e32 v127, 0x18000, v133
	s_waitcnt lgkmcnt(4)
	global_store_dwordx4 v127, v[14:17], s[62:63] offset:1536
	v_add_u32_e32 v126, 0x20000, v133
	s_waitcnt lgkmcnt(3)
	global_store_dwordx4 v126, v[18:21], s[62:63] offset:1536
	v_add_u32_e32 v127, 0x28000, v133
	s_waitcnt lgkmcnt(2)
	global_store_dwordx4 v127, v[22:25], s[62:63] offset:1536
	v_add_u32_e32 v126, 0x30000, v133
	s_waitcnt lgkmcnt(1)
	global_store_dwordx4 v126, v[26:29], s[62:63] offset:1536
	v_add_u32_e32 v127, 0x38000, v133
	s_waitcnt lgkmcnt(0)
	global_store_dwordx4 v127, v[30:33], s[62:63] offset:1536
	s_barrier
	s_cbranch_scc0 .LBB0_849
